# v51: v47 + adaLN: GEMV weight loads for k-batches 1-3 prefetched with batch 0 (one exposed latency instead of four), silu staging loop pipelined
# baseline (speedup 1.0000x reference)
; DI void phase_setup(const Params& p, char* lds) {
;     ...
;         for (int idx = tid; idx < 24 * 512; idx += 256) {
;           const int bi = idx >> 9, k = kh * 512 + (idx & 511);
;           const float c = bi < 8 ? p.c_prompt[bi * D + k] : p.c_sample[(bi - 8) * D + k];
;           cs[idx] = c / (1.0f + expf(-c));
;         }
.LBB0_74:
	v_lshlrev_b32_e32 v3, 1, v0
	v_lshlrev_b32_e32 v2, 1, v1
	v_and_b32_e32 v3, 0x7ffffc00, v3
	v_cmp_gt_u32_e32 vcc, s88, v0
	v_and_b32_e32 v2, 0x7ffffc00, v2
	v_add_u32_e32 v4, 0xffffe000, v3
	v_and_b32_e32 v9, 0x1ff, v0
	v_cmp_gt_u32_e64 s[10:11], s88, v1
	v_add_u32_e32 v5, 0xffffe000, v2
	v_cndmask_b32_e32 v7, v4, v3, vcc
	v_and_b32_e32 v8, 0x1ff, v1
	v_cndmask_b32_e64 v6, v5, v2, s[10:11]
	v_mov_b32_e32 v14, s71
	v_mov_b32_e32 v15, s61
	v_mov_b32_e32 v16, s70
	v_mov_b32_e32 v17, s60
	v_or_b32_e32 v7, v9, v7
	v_mov_b32_e32 v10, s39
	v_mov_b32_e32 v11, s63
	v_mov_b32_e32 v12, s38
	v_mov_b32_e32 v13, s62
	v_cndmask_b32_e32 v5, v14, v15, vcc
	v_cndmask_b32_e32 v4, v16, v17, vcc
	v_or_b32_e32 v6, v8, v6
	v_or_b32_e32 v86, s2, v7
	v_cndmask_b32_e64 v3, v10, v11, s[10:11]
	v_cndmask_b32_e64 v2, v12, v13, s[10:11]
	v_or_b32_e32 v6, s0, v6
	v_lshl_add_u64 v[4:5], v[86:87], 2, v[4:5]
	v_mov_b32_e32 v7, v87
	v_lshl_add_u64 v[2:3], v[6:7], 2, v[2:3]
	global_load_dword v4, v[4:5], off
	s_nop 0
	global_load_dword v5, v[2:3], off
	v_add_u32_e32 v223, 0x200, v0
	v_add_u32_e32 v222, 0x200, v1
	v_cmp_gt_u32_e32 vcc, s88, v223
	v_lshlrev_b32_e32 v223, 1, v223
	v_cmp_gt_u32_e64 s[10:11], s88, v222
	v_lshlrev_b32_e32 v222, 1, v222
	v_and_b32_e32 v223, 0x7ffffc00, v223
	v_and_b32_e32 v222, 0x7ffffc00, v222
	v_add_u32_e32 v224, 0xffffe000, v223
	v_add_u32_e32 v225, 0xffffe000, v222
	v_cndmask_b32_e32 v229, v224, v223, vcc
	v_cndmask_b32_e64 v228, v225, v222, s[10:11]
	v_or_b32_e32 v229, v9, v229
	v_cndmask_b32_e32 v225, v14, v15, vcc
	v_cndmask_b32_e32 v224, v16, v17, vcc
	v_or_b32_e32 v228, v8, v228
	v_or_b32_e32 v86, s2, v229
	v_cndmask_b32_e64 v223, v10, v11, s[10:11]
	v_cndmask_b32_e64 v222, v12, v13, s[10:11]
	v_or_b32_e32 v228, s0, v228
	v_lshl_add_u64 v[224:225], v[86:87], 2, v[224:225]
	v_mov_b32_e32 v229, v87
	v_lshl_add_u64 v[222:223], v[228:229], 2, v[222:223]
	global_load_dword v226, v[224:225], off
	s_nop 0
	global_load_dword v227, v[222:223], off
	v_add_u32_e32 v1, 0x400, v1
	v_add_u32_e32 v0, 0x400, v0
	s_waitcnt vmcnt(2)
	v_mul_f32_e32 v2, 0xbfb8aa3b, v5
	v_fma_f32 v3, v5, s89, -v2
	v_rndne_f32_e32 v6, v2
	v_fmac_f32_e32 v3, 0xb2a5705f, v5
	v_sub_f32_e32 v2, v2, v6
	v_add_f32_e32 v2, v2, v3
	v_exp_f32_e32 v2, v2
	v_cvt_i32_f32_e32 v3, v6
	v_cmp_nlt_f32_e32 vcc, s90, v5
	v_ldexp_f32 v2, v2, v3
	s_nop 0
	v_cndmask_b32_e32 v2, 0, v2, vcc
	v_cmp_ngt_f32_e32 vcc, s91, v5
	s_nop 1
	v_cndmask_b32_e32 v3, v203, v2, vcc
	v_mul_f32_e32 v2, 0xbfb8aa3b, v4
	v_fma_f32 v6, v4, s89, -v2
	v_rndne_f32_e32 v7, v2
	v_fmac_f32_e32 v6, 0xb2a5705f, v4
	v_sub_f32_e32 v2, v2, v7
	v_add_f32_e32 v2, v2, v6
	v_exp_f32_e32 v2, v2
	v_cvt_i32_f32_e32 v6, v7
	v_cmp_nlt_f32_e32 vcc, s90, v4
	v_ldexp_f32 v2, v2, v6
	s_nop 0
	v_cndmask_b32_e32 v2, 0, v2, vcc
	v_cmp_ngt_f32_e32 vcc, s91, v4
	s_nop 1
	v_cndmask_b32_e32 v2, v203, v2, vcc
	v_pk_add_f32 v[2:3], v[2:3], 1.0 op_sel_hi:[1,0]
	s_nop 0
	v_div_scale_f32 v6, s[10:11], v3, v3, v5
	v_rcp_f32_e32 v7, v6
	s_nop 0
	v_fma_f32 v18, -v6, v7, 1.0
	v_fmac_f32_e32 v7, v18, v7
	v_div_scale_f32 v18, vcc, v5, v3, v5
	v_mul_f32_e32 v19, v18, v7
	v_fma_f32 v20, -v6, v19, v18
	v_fmac_f32_e32 v19, v20, v7
	v_fma_f32 v6, -v6, v19, v18
	v_div_fmas_f32 v6, v6, v7, v19
	v_div_fixup_f32 v3, v6, v3, v5
	v_div_scale_f32 v5, s[10:11], v2, v2, v4
	v_rcp_f32_e32 v6, v5
	s_nop 0
	v_fma_f32 v7, -v5, v6, 1.0
	v_fmac_f32_e32 v6, v7, v6
	v_div_scale_f32 v7, vcc, v4, v2, v4
	v_mul_f32_e32 v18, v7, v6
	v_fma_f32 v19, -v5, v18, v7
	v_fmac_f32_e32 v18, v19, v6
	v_fma_f32 v5, -v5, v18, v7
	v_div_fmas_f32 v5, v5, v6, v18
	v_div_fixup_f32 v2, v5, v2, v4
	v_add_u32_e32 v4, s1, v153
	ds_write2st64_b32 v4, v2, v3 offset1:4
	s_waitcnt vmcnt(0)
	v_mov_b32_e32 v4, v226
	v_mov_b32_e32 v5, v227
	v_mul_f32_e32 v2, 0xbfb8aa3b, v5
	v_fma_f32 v3, v5, s89, -v2
	v_rndne_f32_e32 v6, v2
	v_fmac_f32_e32 v3, 0xb2a5705f, v5
	v_sub_f32_e32 v2, v2, v6
	v_add_f32_e32 v2, v2, v3
	v_exp_f32_e32 v2, v2
	v_cvt_i32_f32_e32 v3, v6
	v_cmp_nlt_f32_e32 vcc, s90, v5
	v_ldexp_f32 v2, v2, v3
	s_nop 0
	v_cndmask_b32_e32 v2, 0, v2, vcc
	v_cmp_ngt_f32_e32 vcc, s91, v5
	s_nop 1
	v_cndmask_b32_e32 v3, v203, v2, vcc
	v_mul_f32_e32 v2, 0xbfb8aa3b, v4
	v_fma_f32 v6, v4, s89, -v2
	v_rndne_f32_e32 v7, v2
	v_fmac_f32_e32 v6, 0xb2a5705f, v4
	v_sub_f32_e32 v2, v2, v7
	v_add_f32_e32 v2, v2, v6
	v_exp_f32_e32 v2, v2
	v_cvt_i32_f32_e32 v6, v7
	v_cmp_nlt_f32_e32 vcc, s90, v4
	v_ldexp_f32 v2, v2, v6
	s_nop 0
	v_cndmask_b32_e32 v2, 0, v2, vcc
	v_cmp_ngt_f32_e32 vcc, s91, v4
	s_nop 1
	v_cndmask_b32_e32 v2, v203, v2, vcc
	v_pk_add_f32 v[2:3], v[2:3], 1.0 op_sel_hi:[1,0]
	s_nop 0
	v_div_scale_f32 v6, s[10:11], v3, v3, v5
	v_rcp_f32_e32 v7, v6
	s_nop 0
	v_fma_f32 v8, -v6, v7, 1.0
	v_fmac_f32_e32 v7, v8, v7
	v_div_scale_f32 v8, vcc, v5, v3, v5
	v_mul_f32_e32 v9, v8, v7
	v_fma_f32 v10, -v6, v9, v8
	v_fmac_f32_e32 v9, v10, v7
	v_fma_f32 v6, -v6, v9, v8
	v_div_fmas_f32 v6, v6, v7, v9
	v_div_fixup_f32 v3, v6, v3, v5
	v_div_scale_f32 v5, s[10:11], v2, v2, v4
	v_rcp_f32_e32 v6, v5
	s_nop 0
	v_fma_f32 v7, -v5, v6, 1.0
	v_fmac_f32_e32 v6, v7, v6
	v_div_scale_f32 v7, vcc, v4, v2, v4
	v_mul_f32_e32 v8, v7, v6
	v_fma_f32 v9, -v5, v8, v7
	v_fmac_f32_e32 v8, v9, v6
	v_fma_f32 v5, -v5, v8, v7
	v_div_fmas_f32 v5, v5, v6, v8
	v_div_fixup_f32 v2, v5, v2, v4
	v_add_u32_e32 v4, s1, v197
	s_addk_i32 s1, 0x1000
	s_cmpk_lg_u32 s1, 0xc000
	ds_write2st64_b32 v4, v2, v3 offset1:4
	s_cbranch_scc1 .LBB0_74
	v_or_b32_e32 v0, s2, v102
	v_mad_u64_u32 v[106:107], s[0:1], v0, s92, v[104:105]
	v_mad_i32_i24 v107, v103, s92, v107
	v_add_co_u32_e32 v0, vcc, 0x3000, v106
	s_waitcnt lgkmcnt(0)
	s_nop 0
	v_addc_co_u32_e32 v1, vcc, 0, v107, vcc
	s_barrier
; DI void phase_setup(const Params& p, char* lds) {
;     ...
;         const float* wp = p.w_ada + ((size_t)layer * D + kh * 512 + kp * 32) * 3072 + cc * 16 + col;
; #pragma unroll
;         for (int k8 = 0; k8 < 32; k8 += 8) {
;           float w[8];
; #pragma unroll
;           for (int u = 0; u < 8; ++u) w[u] = wp[(size_t)(k8 + u) * 3072];
; #pragma unroll
;           for (int bi = 0; bi < 24; ++bi) {
;             const float4 c0 = *(const float4*)(cs + bi * 512 + kp * 32 + k8), c1 = *(const float4*)(cs + bi * 512 + kp * 32 + k8 + 4);
;             acc[bi] += c0.x * w[0] + c0.y * w[1] + c0.z * w[2] + c0.w * w[3] + c1.x * w[4] + c1.y * w[5] + c1.z * w[6] + c1.w * w[7];
	global_load_dword v86, v[106:107], off
	global_load_dword v152, v[0:1], off
	v_add_co_u32_e32 v0, vcc, 0x6000, v106
	s_mov_b32 s0, 0xc000
	s_nop 0
	v_addc_co_u32_e32 v1, vcc, 0, v107, vcc
	global_load_dword v132, v[0:1], off
	v_add_co_u32_e32 v0, vcc, 0x9000, v106
	s_movk_i32 s2, 0x200
	s_nop 0
	v_addc_co_u32_e32 v1, vcc, 0, v107, vcc
	global_load_dword v134, v[0:1], off
	v_add_co_u32_e32 v0, vcc, s0, v106
	s_mov_b32 s0, 0x18000
	s_nop 0
	v_addc_co_u32_e32 v1, vcc, 0, v107, vcc
	global_load_dword v136, v[0:1], off
	v_add_co_u32_e32 v0, vcc, 0xf000, v106
	s_nop 1
	v_addc_co_u32_e32 v1, vcc, 0, v107, vcc
	global_load_dword v138, v[0:1], off
	v_add_co_u32_e32 v0, vcc, 0x12000, v106
	s_nop 1
	v_addc_co_u32_e32 v1, vcc, 0, v107, vcc
	global_load_dword v140, v[0:1], off
	v_add_co_u32_e32 v0, vcc, 0x15000, v106
	s_nop 1
	v_addc_co_u32_e32 v1, vcc, 0, v107, vcc
	global_load_dword v142, v[0:1], off
	s_mov_b64 s[98:99], 0x18000
	v_lshl_add_u64 v[248:249], v[106:107], 0, s[98:99]
	s_mov_b64 s[98:99], 0x3000
	global_load_dword v218, v[248:249], off
	v_lshl_add_u64 v[248:249], v[248:249], 0, s[98:99]
	global_load_dword v219, v[248:249], off
	v_lshl_add_u64 v[248:249], v[248:249], 0, s[98:99]
	global_load_dword v220, v[248:249], off
	v_lshl_add_u64 v[248:249], v[248:249], 0, s[98:99]
	global_load_dword v221, v[248:249], off
	v_lshl_add_u64 v[248:249], v[248:249], 0, s[98:99]
	global_load_dword v222, v[248:249], off
	v_lshl_add_u64 v[248:249], v[248:249], 0, s[98:99]
	global_load_dword v223, v[248:249], off
	v_lshl_add_u64 v[248:249], v[248:249], 0, s[98:99]
	global_load_dword v224, v[248:249], off
	v_lshl_add_u64 v[248:249], v[248:249], 0, s[98:99]
	global_load_dword v225, v[248:249], off
	v_lshl_add_u64 v[248:249], v[248:249], 0, s[98:99]
	global_load_dword v226, v[248:249], off
	v_lshl_add_u64 v[248:249], v[248:249], 0, s[98:99]
	global_load_dword v227, v[248:249], off
	v_lshl_add_u64 v[248:249], v[248:249], 0, s[98:99]
	global_load_dword v228, v[248:249], off
	v_lshl_add_u64 v[248:249], v[248:249], 0, s[98:99]
	global_load_dword v229, v[248:249], off
	v_lshl_add_u64 v[248:249], v[248:249], 0, s[98:99]
	global_load_dword v230, v[248:249], off
	v_lshl_add_u64 v[248:249], v[248:249], 0, s[98:99]
	global_load_dword v231, v[248:249], off
	v_lshl_add_u64 v[248:249], v[248:249], 0, s[98:99]
	global_load_dword v232, v[248:249], off
	v_lshl_add_u64 v[248:249], v[248:249], 0, s[98:99]
	global_load_dword v233, v[248:249], off
	v_lshl_add_u64 v[248:249], v[248:249], 0, s[98:99]
	global_load_dword v234, v[248:249], off
	v_lshl_add_u64 v[248:249], v[248:249], 0, s[98:99]
	global_load_dword v235, v[248:249], off
	v_lshl_add_u64 v[248:249], v[248:249], 0, s[98:99]
	global_load_dword v236, v[248:249], off
	v_lshl_add_u64 v[248:249], v[248:249], 0, s[98:99]
	global_load_dword v237, v[248:249], off
	v_lshl_add_u64 v[248:249], v[248:249], 0, s[98:99]
	global_load_dword v238, v[248:249], off
	v_lshl_add_u64 v[248:249], v[248:249], 0, s[98:99]
	global_load_dword v239, v[248:249], off
	v_lshl_add_u64 v[248:249], v[248:249], 0, s[98:99]
	global_load_dword v240, v[248:249], off
	v_lshl_add_u64 v[248:249], v[248:249], 0, s[98:99]
	global_load_dword v241, v[248:249], off
	ds_read_b128 v[14:17], v143
	ds_read_b128 v[74:77], v143 offset:16
	ds_read_b128 v[50:53], v143 offset:32
	ds_read_b128 v[46:49], v143 offset:48
	ds_read_b128 v[78:81], v143 offset:2048
	ds_read_b128 v[18:21], v143 offset:4096
	ds_read_b128 v[70:73], v143 offset:6144
	ds_read_b128 v[28:31], v143 offset:8192
	ds_read_b128 v[60:63], v143 offset:10240
	s_waitcnt lgkmcnt(8)
	v_mov_b32_e32 v164, v14
	s_waitcnt lgkmcnt(4)
	v_mov_b32_e32 v165, v78
	s_waitcnt lgkmcnt(2)
	v_mov_b32_e32 v161, v70
	v_mov_b32_e32 v70, v19
	s_waitcnt lgkmcnt(0)
	v_mov_b32_e32 v155, v60
	v_mov_b32_e32 v60, v29
	v_mov_b32_e32 v154, v28
	v_mov_b32_e32 v78, v15
	v_mov_b32_e32 v160, v18
	s_waitcnt vmcnt(30)
	v_pk_mul_f32 v[162:163], v[152:153], v[70:71] op_sel_hi:[0,1]
	v_pk_mul_f32 v[156:157], v[152:153], v[60:61] op_sel_hi:[0,1]
	ds_read_b128 v[64:67], v143 offset:12288
	ds_read_b128 v[68:71], v143 offset:14336
	ds_read_b128 v[54:57], v143 offset:16384
	ds_read_b128 v[58:61], v143 offset:18432
	ds_read_b128 v[38:41], v143 offset:20480
	ds_read_b128 v[42:45], v143 offset:22528
	v_pk_mul_f32 v[166:167], v[152:153], v[78:79] op_sel_hi:[0,1]
	s_waitcnt lgkmcnt(5)
	v_mov_b32_e32 v158, v64
	s_waitcnt lgkmcnt(4)
	v_mov_b32_e32 v159, v68
	s_waitcnt lgkmcnt(1)
	v_mov_b32_e32 v144, v38
	s_waitcnt lgkmcnt(0)
	v_mov_b32_e32 v145, v42
	v_mov_b32_e32 v42, v39
	ds_read_b128 v[32:35], v143 offset:24576
	ds_read_b128 v[36:39], v143 offset:26624
	ds_read_b128 v[22:25], v143 offset:28672
	ds_read_b128 v[26:29], v143 offset:30720
	ds_read_b128 v[8:11], v143 offset:32768
	ds_read_b128 v[12:15], v143 offset:34816
	v_mov_b32_e32 v149, v58
	v_mov_b32_e32 v58, v55
	v_pk_mul_f32 v[150:151], v[152:153], v[58:59] op_sel_hi:[0,1]
	s_waitcnt lgkmcnt(2)
	v_mov_b32_e32 v55, v26
	v_mov_b32_e32 v26, v23
	v_pk_mul_f32 v[58:59], v[152:153], v[26:27] op_sel_hi:[0,1]
	s_waitcnt lgkmcnt(1)
	v_mov_b32_e32 v26, v8
	s_waitcnt lgkmcnt(0)
	v_mov_b32_e32 v27, v12
	v_mov_b32_e32 v12, v9
	ds_read_b128 v[2:5], v143 offset:36864
	ds_read_b128 v[6:9], v143 offset:38912
	v_mov_b32_e32 v68, v65
	v_pk_mul_f32 v[64:65], v[152:153], v[68:69] op_sel_hi:[0,1]
	v_mov_b32_e32 v69, v36
	v_mov_b32_e32 v36, v33
	v_pk_mul_f32 v[78:79], v[152:153], v[36:37] op_sel_hi:[0,1]
	v_pk_mul_f32 v[36:37], v[152:153], v[12:13] op_sel_hi:[0,1]
	s_waitcnt lgkmcnt(1)
	v_mov_b32_e32 v12, v2
	s_waitcnt lgkmcnt(0)
; DI void phase_setup(const Params& p, char* lds) {
;     ...
;         for (int k8 = 0; k8 < 32; k8 += 8) {
;           float w[8];
; #pragma unroll
;           for (int u = 0; u < 8; ++u) w[u] = wp[(size_t)(k8 + u) * 3072];
; #pragma unroll
;           for (int bi = 0; bi < 24; ++bi) {
;             const float4 c0 = *(const float4*)(cs + bi * 512 + kp * 32 + k8), c1 = *(const float4*)(cs + bi * 512 + kp * 32 + k8 + 4);
;             acc[bi] += c0.x * w[0] + c0.y * w[1] + c0.z * w[2] + c0.w * w[3] + c1.x * w[4] + c1.y * w[5] + c1.z * w[6] + c1.w * w[7];
;           }
	v_mov_b32_e32 v13, v6
	v_mov_b32_e32 v6, v3
	ds_read_b128 v[0:3], v143 offset:40960
	ds_read_b128 v[214:217], v143 offset:2064
	v_mov_b32_e32 v148, v54
	v_mov_b32_e32 v54, v22
	v_pk_fma_f32 v[18:19], v[86:87], v[164:165], v[166:167] op_sel_hi:[0,1,1]
	v_mov_b32_e32 v22, v16
	v_mov_b32_e32 v23, v80
	s_waitcnt vmcnt(29)
	v_pk_fma_f32 v[18:19], v[132:133], v[22:23], v[18:19] op_sel_hi:[0,1,1]
	v_mov_b32_e32 v80, v17
	s_waitcnt vmcnt(28)
	v_pk_fma_f32 v[16:17], v[134:135], v[80:81], v[18:19] op_sel_hi:[0,1,1]
	v_mov_b32_e32 v18, v74
	s_waitcnt lgkmcnt(0)
	v_mov_b32_e32 v19, v214
	s_waitcnt vmcnt(27)
	v_pk_fma_f32 v[16:17], v[136:137], v[18:19], v[16:17] op_sel_hi:[0,1,1]
	v_mov_b32_e32 v214, v75
	s_waitcnt vmcnt(26)
	v_pk_fma_f32 v[16:17], v[138:139], v[214:215], v[16:17] op_sel_hi:[0,1,1]
	v_mov_b32_e32 v18, v76
	v_mov_b32_e32 v19, v216
	s_waitcnt vmcnt(25)
	v_pk_fma_f32 v[16:17], v[140:141], v[18:19], v[16:17] op_sel_hi:[0,1,1]
	v_mov_b32_e32 v216, v77
	s_waitcnt vmcnt(24)
	v_pk_fma_f32 v[16:17], v[142:143], v[216:217], v[16:17] op_sel_hi:[0,1,1]
	v_pk_add_f32 v[130:131], v[130:131], v[16:17]
	ds_read_b128 v[16:19], v143 offset:43008
	ds_read_b128 v[74:77], v143 offset:4112
	ds_read_b128 v[164:167], v143 offset:6160
	v_pk_mul_f32 v[146:147], v[152:153], v[42:43] op_sel_hi:[0,1]
	v_mov_b32_e32 v42, v0
	v_mov_b32_e32 v22, v20
	s_waitcnt lgkmcnt(2)
	v_mov_b32_e32 v43, v16
	v_mov_b32_e32 v16, v1
	v_pk_mul_f32 v[0:1], v[152:153], v[16:17] op_sel_hi:[0,1]
	v_pk_fma_f32 v[16:17], v[86:87], v[160:161], v[162:163] op_sel_hi:[0,1,1]
	v_mov_b32_e32 v23, v72
	v_pk_fma_f32 v[16:17], v[132:133], v[22:23], v[16:17] op_sel_hi:[0,1,1]
	v_mov_b32_e32 v72, v21
	v_pk_fma_f32 v[16:17], v[134:135], v[72:73], v[16:17] op_sel_hi:[0,1,1]
	s_waitcnt lgkmcnt(1)
	v_mov_b32_e32 v20, v74
	s_waitcnt lgkmcnt(0)
	v_mov_b32_e32 v21, v164
	v_pk_fma_f32 v[16:17], v[136:137], v[20:21], v[16:17] op_sel_hi:[0,1,1]
	v_mov_b32_e32 v164, v75
	v_pk_fma_f32 v[16:17], v[138:139], v[164:165], v[16:17] op_sel_hi:[0,1,1]
	v_mov_b32_e32 v20, v76
	v_mov_b32_e32 v21, v166
	v_pk_fma_f32 v[16:17], v[140:141], v[20:21], v[16:17] op_sel_hi:[0,1,1]
	ds_read_b128 v[20:23], v143 offset:45056
	ds_read_b128 v[72:75], v143 offset:8208
	ds_read_b128 v[160:163], v143 offset:10256
	v_mov_b32_e32 v166, v77
	v_pk_fma_f32 v[16:17], v[142:143], v[166:167], v[16:17] op_sel_hi:[0,1,1]
	v_mov_b32_e32 v68, v32
	v_pk_add_f32 v[126:127], v[126:127], v[16:17]
	v_pk_fma_f32 v[16:17], v[86:87], v[154:155], v[156:157] op_sel_hi:[0,1,1]
	v_mov_b32_e32 v32, v30
	v_mov_b32_e32 v33, v62
	v_pk_fma_f32 v[16:17], v[132:133], v[32:33], v[16:17] op_sel_hi:[0,1,1]
	v_mov_b32_e32 v62, v31
	v_pk_fma_f32 v[16:17], v[134:135], v[62:63], v[16:17] op_sel_hi:[0,1,1]
	s_waitcnt lgkmcnt(1)
	v_mov_b32_e32 v30, v72
	s_waitcnt lgkmcnt(0)
	v_mov_b32_e32 v31, v160
	v_pk_fma_f32 v[16:17], v[136:137], v[30:31], v[16:17] op_sel_hi:[0,1,1]
	v_mov_b32_e32 v160, v73
	v_pk_fma_f32 v[16:17], v[138:139], v[160:161], v[16:17] op_sel_hi:[0,1,1]
	v_mov_b32_e32 v30, v74
	v_mov_b32_e32 v31, v162
	v_pk_fma_f32 v[16:17], v[140:141], v[30:31], v[16:17] op_sel_hi:[0,1,1]
	ds_read_b128 v[30:33], v143 offset:47104
	v_mov_b32_e32 v162, v75
	ds_read_b128 v[72:75], v143 offset:12304
	ds_read_b128 v[154:157], v143 offset:14352
	v_pk_fma_f32 v[16:17], v[142:143], v[162:163], v[16:17] op_sel_hi:[0,1,1]
	v_pk_add_f32 v[124:125], v[124:125], v[16:17]
	s_waitcnt lgkmcnt(2)
	v_mov_b32_e32 v17, v30
	v_mov_b32_e32 v30, v21
	v_mov_b32_e32 v16, v20
	v_pk_mul_f32 v[20:21], v[152:153], v[30:31] op_sel_hi:[0,1]
	v_pk_fma_f32 v[30:31], v[86:87], v[158:159], v[64:65] op_sel_hi:[0,1,1]
	v_mov_b32_e32 v62, v66
	v_mov_b32_e32 v63, v70
	v_pk_fma_f32 v[30:31], v[132:133], v[62:63], v[30:31] op_sel_hi:[0,1,1]
	v_mov_b32_e32 v70, v67
	v_pk_fma_f32 v[30:31], v[134:135], v[70:71], v[30:31] op_sel_hi:[0,1,1]
	s_waitcnt lgkmcnt(1)
	v_mov_b32_e32 v62, v72
	s_waitcnt lgkmcnt(0)
	v_mov_b32_e32 v63, v154
	v_pk_fma_f32 v[30:31], v[136:137], v[62:63], v[30:31] op_sel_hi:[0,1,1]
	v_mov_b32_e32 v154, v73
	v_pk_fma_f32 v[30:31], v[138:139], v[154:155], v[30:31] op_sel_hi:[0,1,1]
	v_mov_b32_e32 v62, v74
	v_mov_b32_e32 v63, v156
	v_pk_fma_f32 v[30:31], v[140:141], v[62:63], v[30:31] op_sel_hi:[0,1,1]
	v_mov_b32_e32 v156, v75
	v_pk_fma_f32 v[30:31], v[142:143], v[156:157], v[30:31] op_sel_hi:[0,1,1]
	v_pk_add_f32 v[80:81], v[128:129], v[30:31]
	v_add_co_u32_e32 v30, vcc, s0, v106
	s_mov_b32 s0, 0x1b000
	s_nop 0
	v_addc_co_u32_e32 v31, vcc, 0, v107, vcc
	v_add_co_u32_e32 v62, vcc, s0, v106
	s_mov_b32 s0, 0x1e000
	s_nop 0
	v_addc_co_u32_e32 v63, vcc, 0, v107, vcc
	v_add_co_u32_e32 v64, vcc, s0, v106
	s_mov_b32 s0, 0x21000
	s_nop 0
	v_addc_co_u32_e32 v65, vcc, 0, v107, vcc
	v_add_co_u32_e32 v66, vcc, s0, v106
	s_mov_b32 s0, 0x24000
	s_nop 0
	v_addc_co_u32_e32 v67, vcc, 0, v107, vcc
	v_add_co_u32_e32 v70, vcc, s0, v106
	s_waitcnt vmcnt(16)
	v_mov_b32_e32 v30, v218
	s_nop 0
	v_addc_co_u32_e32 v71, vcc, 0, v107, vcc
	v_mov_b32_e32 v62, v219
	s_mov_b32 s0, 0x27000
	v_add_co_u32_e32 v72, vcc, s0, v106
	v_mov_b32_e32 v64, v220
	s_nop 0
	v_addc_co_u32_e32 v73, vcc, 0, v107, vcc
	s_mov_b32 s0, 0x2a000
	v_mov_b32_e32 v66, v221
	v_add_co_u32_e32 v74, vcc, s0, v106
	v_mov_b32_e32 v70, v222
	s_nop 0
	v_addc_co_u32_e32 v75, vcc, 0, v107, vcc
	s_mov_b32 s0, 0x2d000
	v_mov_b32_e32 v72, v223
	v_add_co_u32_e32 v76, vcc, s0, v106
	v_mov_b32_e32 v74, v224
	s_nop 0
	v_addc_co_u32_e32 v77, vcc, 0, v107, vcc
	v_mov_b32_e32 v76, v225
	ds_read_b128 v[154:157], v143 offset:16400
	ds_read_b128 v[158:161], v143 offset:18448
	v_pk_fma_f32 v[128:129], v[86:87], v[148:149], v[150:151] op_sel_hi:[0,1,1]
	v_mov_b32_e32 v148, v56
	v_mov_b32_e32 v149, v60
	v_pk_fma_f32 v[128:129], v[132:133], v[148:149], v[128:129] op_sel_hi:[0,1,1]
	v_mov_b32_e32 v60, v57
	v_pk_fma_f32 v[56:57], v[134:135], v[60:61], v[128:129] op_sel_hi:[0,1,1]
	s_waitcnt lgkmcnt(1)
; DI void phase_setup(const Params& p, char* lds) {
;     ...
;         for (int k8 = 0; k8 < 32; k8 += 8) {
;           float w[8];
; #pragma unroll
;           for (int u = 0; u < 8; ++u) w[u] = wp[(size_t)(k8 + u) * 3072];
; #pragma unroll
;           for (int bi = 0; bi < 24; ++bi) {
;             const float4 c0 = *(const float4*)(cs + bi * 512 + kp * 32 + k8), c1 = *(const float4*)(cs + bi * 512 + kp * 32 + k8 + 4);
;             acc[bi] += c0.x * w[0] + c0.y * w[1] + c0.z * w[2] + c0.w * w[3] + c1.x * w[4] + c1.y * w[5] + c1.z * w[6] + c1.w * w[7];
;           }
	v_mov_b32_e32 v60, v154
	s_waitcnt lgkmcnt(0)
	v_mov_b32_e32 v61, v158
	v_pk_fma_f32 v[56:57], v[136:137], v[60:61], v[56:57] op_sel_hi:[0,1,1]
	v_mov_b32_e32 v158, v155
	v_mov_b32_e32 v60, v156
	v_mov_b32_e32 v61, v160
	v_mov_b32_e32 v160, v157
	ds_read_b128 v[148:151], v143 offset:2080
	ds_read_b128 v[154:157], v143 offset:2096
	v_pk_fma_f32 v[56:57], v[138:139], v[158:159], v[56:57] op_sel_hi:[0,1,1]
	v_pk_fma_f32 v[56:57], v[140:141], v[60:61], v[56:57] op_sel_hi:[0,1,1]
	v_mov_b32_e32 v60, v50
	s_waitcnt lgkmcnt(1)
	v_mov_b32_e32 v61, v148
	v_mov_b32_e32 v148, v51
	v_pk_fma_f32 v[56:57], v[142:143], v[160:161], v[56:57] op_sel_hi:[0,1,1]
	v_pk_add_f32 v[56:57], v[122:123], v[56:57]
	v_pk_fma_f32 v[54:55], v[86:87], v[54:55], v[58:59] op_sel_hi:[0,1,1]
	v_mov_b32_e32 v58, v24
	v_mov_b32_e32 v59, v28
	v_pk_fma_f32 v[54:55], v[132:133], v[58:59], v[54:55] op_sel_hi:[0,1,1]
	v_mov_b32_e32 v28, v25
	v_pk_fma_f32 v[24:25], v[134:135], v[28:29], v[54:55] op_sel_hi:[0,1,1]
	v_pk_fma_f32 v[26:27], v[86:87], v[26:27], v[36:37] op_sel_hi:[0,1,1]
	v_mov_b32_e32 v36, v10
	v_mov_b32_e32 v37, v14
	v_pk_fma_f32 v[26:27], v[132:133], v[36:37], v[26:27] op_sel_hi:[0,1,1]
	v_mov_b32_e32 v14, v11
	v_pk_fma_f32 v[10:11], v[134:135], v[14:15], v[26:27] op_sel_hi:[0,1,1]
	v_pk_mul_f32 v[6:7], v[152:153], v[6:7] op_sel_hi:[0,1]
	v_pk_fma_f32 v[6:7], v[86:87], v[12:13], v[6:7] op_sel_hi:[0,1,1]
	v_mov_b32_e32 v12, v4
	v_mov_b32_e32 v13, v8
	v_pk_fma_f32 v[6:7], v[132:133], v[12:13], v[6:7] op_sel_hi:[0,1,1]
	v_mov_b32_e32 v8, v5
	v_pk_fma_f32 v[4:5], v[134:135], v[8:9], v[6:7] op_sel_hi:[0,1,1]
	v_pk_fma_f32 v[0:1], v[86:87], v[42:43], v[0:1] op_sel_hi:[0,1,1]
	v_pk_fma_f32 v[16:17], v[86:87], v[16:17], v[20:21] op_sel_hi:[0,1,1]
	s_mov_b32 s0, 0x30000
	s_waitcnt vmcnt(22)
	v_pk_mul_f32 v[50:51], v[62:63], v[148:149] op_sel_hi:[0,1]
	v_pk_fma_f32 v[50:51], v[30:31], v[60:61], v[50:51] op_sel_hi:[0,1,1]
	v_mov_b32_e32 v60, v52
	v_mov_b32_e32 v61, v150
	s_waitcnt vmcnt(21)
	v_pk_fma_f32 v[50:51], v[64:65], v[60:61], v[50:51] op_sel_hi:[0,1,1]
	v_mov_b32_e32 v150, v53
	v_mov_b32_e32 v52, v46
	s_waitcnt lgkmcnt(0)
	v_mov_b32_e32 v53, v154
	s_waitcnt vmcnt(20)
	v_pk_fma_f32 v[50:51], v[66:67], v[150:151], v[50:51] op_sel_hi:[0,1,1]
	v_mov_b32_e32 v154, v47
	v_mov_b32_e32 v60, v40
	s_waitcnt vmcnt(19)
	v_pk_fma_f32 v[50:51], v[70:71], v[52:53], v[50:51] op_sel_hi:[0,1,1]
	v_pk_fma_f32 v[52:53], v[86:87], v[144:145], v[146:147] op_sel_hi:[0,1,1]
	v_mov_b32_e32 v61, v44
	v_pk_fma_f32 v[52:53], v[132:133], v[60:61], v[52:53] op_sel_hi:[0,1,1]
	s_waitcnt vmcnt(18)
	v_pk_fma_f32 v[46:47], v[72:73], v[154:155], v[50:51] op_sel_hi:[0,1,1]
	v_mov_b32_e32 v50, v48
	v_mov_b32_e32 v51, v156
	s_waitcnt vmcnt(17)
	v_pk_fma_f32 v[46:47], v[74:75], v[50:51], v[46:47] op_sel_hi:[0,1,1]
	v_mov_b32_e32 v156, v49
	v_mov_b32_e32 v44, v41
	s_waitcnt vmcnt(16)
	v_pk_fma_f32 v[46:47], v[76:77], v[156:157], v[46:47] op_sel_hi:[0,1,1]
	v_pk_add_f32 v[46:47], v[130:131], v[46:47]
	ds_read_b128 v[48:51], v143 offset:4128
	ds_read_b128 v[128:131], v143 offset:4144
	ds_read_b128 v[148:151], v143 offset:20496
	ds_read_b128 v[154:157], v143 offset:22544
	v_pk_fma_f32 v[40:41], v[134:135], v[44:45], v[52:53] op_sel_hi:[0,1,1]
	s_waitcnt lgkmcnt(1)
	v_mov_b32_e32 v44, v148
	s_waitcnt lgkmcnt(0)
	v_mov_b32_e32 v45, v154
	v_pk_fma_f32 v[40:41], v[136:137], v[44:45], v[40:41] op_sel_hi:[0,1,1]
	v_mov_b32_e32 v154, v149
	v_pk_fma_f32 v[40:41], v[138:139], v[154:155], v[40:41] op_sel_hi:[0,1,1]
	v_mov_b32_e32 v44, v150
	v_mov_b32_e32 v45, v156
	v_pk_fma_f32 v[40:41], v[140:141], v[44:45], v[40:41] op_sel_hi:[0,1,1]
	v_mov_b32_e32 v156, v151
	v_pk_fma_f32 v[40:41], v[142:143], v[156:157], v[40:41] op_sel_hi:[0,1,1]
	v_pk_add_f32 v[44:45], v[120:121], v[40:41]
	ds_read_b128 v[120:123], v143 offset:6176
	ds_read_b128 v[144:147], v143 offset:6192
	v_mov_b32_e32 v40, v48
	s_waitcnt lgkmcnt(1)
	v_mov_b32_e32 v41, v120
	v_mov_b32_e32 v120, v49
	v_pk_mul_f32 v[48:49], v[62:63], v[120:121] op_sel_hi:[0,1]
	v_pk_fma_f32 v[40:41], v[30:31], v[40:41], v[48:49] op_sel_hi:[0,1,1]
	v_mov_b32_e32 v48, v50
	v_mov_b32_e32 v49, v122
	v_pk_fma_f32 v[40:41], v[64:65], v[48:49], v[40:41] op_sel_hi:[0,1,1]
	v_mov_b32_e32 v122, v51
	v_pk_fma_f32 v[40:41], v[66:67], v[122:123], v[40:41] op_sel_hi:[0,1,1]
	v_mov_b32_e32 v48, v128
	s_waitcnt lgkmcnt(0)
	v_mov_b32_e32 v49, v144
	v_pk_fma_f32 v[40:41], v[70:71], v[48:49], v[40:41] op_sel_hi:[0,1,1]
	v_mov_b32_e32 v144, v129
	v_pk_fma_f32 v[40:41], v[72:73], v[144:145], v[40:41] op_sel_hi:[0,1,1]
	v_mov_b32_e32 v48, v130
	v_mov_b32_e32 v49, v146
	v_pk_fma_f32 v[40:41], v[74:75], v[48:49], v[40:41] op_sel_hi:[0,1,1]
	v_mov_b32_e32 v146, v131
	v_pk_fma_f32 v[40:41], v[76:77], v[146:147], v[40:41] op_sel_hi:[0,1,1]
	v_pk_add_f32 v[40:41], v[126:127], v[40:41]
	ds_read_b128 v[48:51], v143 offset:8224
	ds_read_b128 v[120:123], v143 offset:8240
	ds_read_b128 v[126:129], v143 offset:10272
	s_waitcnt lgkmcnt(2)
	v_mov_b32_e32 v52, v48
	s_waitcnt lgkmcnt(0)
	v_mov_b32_e32 v53, v126
	v_mov_b32_e32 v126, v49
	v_pk_mul_f32 v[48:49], v[62:63], v[126:127] op_sel_hi:[0,1]
	v_pk_fma_f32 v[48:49], v[30:31], v[52:53], v[48:49] op_sel_hi:[0,1,1]
	v_mov_b32_e32 v52, v50
	v_mov_b32_e32 v53, v128
	v_pk_fma_f32 v[48:49], v[64:65], v[52:53], v[48:49] op_sel_hi:[0,1,1]
	v_mov_b32_e32 v128, v51
	v_pk_fma_f32 v[60:61], v[66:67], v[128:129], v[48:49] op_sel_hi:[0,1,1]
	ds_read_b128 v[48:51], v143 offset:24592
	ds_read_b128 v[126:129], v143 offset:26640
	v_pk_fma_f32 v[52:53], v[86:87], v[68:69], v[78:79] op_sel_hi:[0,1,1]
	v_mov_b32_e32 v68, v34
	v_mov_b32_e32 v69, v38
	v_pk_fma_f32 v[52:53], v[132:133], v[68:69], v[52:53] op_sel_hi:[0,1,1]
	v_mov_b32_e32 v38, v35
	v_pk_fma_f32 v[34:35], v[134:135], v[38:39], v[52:53] op_sel_hi:[0,1,1]
	s_waitcnt lgkmcnt(1)
; DI void phase_setup(const Params& p, char* lds) {
;     ...
;         for (int k8 = 0; k8 < 32; k8 += 8) {
;           float w[8];
; #pragma unroll
;           for (int u = 0; u < 8; ++u) w[u] = wp[(size_t)(k8 + u) * 3072];
; #pragma unroll
;           for (int bi = 0; bi < 24; ++bi) {
;             const float4 c0 = *(const float4*)(cs + bi * 512 + kp * 32 + k8), c1 = *(const float4*)(cs + bi * 512 + kp * 32 + k8 + 4);
;             acc[bi] += c0.x * w[0] + c0.y * w[1] + c0.z * w[2] + c0.w * w[3] + c1.x * w[4] + c1.y * w[5] + c1.z * w[6] + c1.w * w[7];
;           }
	v_mov_b32_e32 v38, v48
	s_waitcnt lgkmcnt(0)
	v_mov_b32_e32 v39, v126
	v_pk_fma_f32 v[34:35], v[136:137], v[38:39], v[34:35] op_sel_hi:[0,1,1]
	v_mov_b32_e32 v38, v50
	v_mov_b32_e32 v39, v128
	v_mov_b32_e32 v128, v51
	ds_read_b128 v[50:53], v143 offset:10288
	v_mov_b32_e32 v126, v49
	v_pk_fma_f32 v[34:35], v[138:139], v[126:127], v[34:35] op_sel_hi:[0,1,1]
	v_pk_fma_f32 v[34:35], v[140:141], v[38:39], v[34:35] op_sel_hi:[0,1,1]
	v_pk_fma_f32 v[34:35], v[142:143], v[128:129], v[34:35] op_sel_hi:[0,1,1]
	v_pk_add_f32 v[48:49], v[118:119], v[34:35]
	v_mov_b32_e32 v34, v120
	s_waitcnt lgkmcnt(0)
	v_mov_b32_e32 v35, v50
	v_pk_fma_f32 v[34:35], v[70:71], v[34:35], v[60:61] op_sel_hi:[0,1,1]
	v_mov_b32_e32 v50, v121
	v_pk_fma_f32 v[34:35], v[72:73], v[50:51], v[34:35] op_sel_hi:[0,1,1]
	v_mov_b32_e32 v38, v122
	v_mov_b32_e32 v39, v52
	v_pk_fma_f32 v[34:35], v[74:75], v[38:39], v[34:35] op_sel_hi:[0,1,1]
	v_mov_b32_e32 v52, v123
	v_pk_fma_f32 v[34:35], v[76:77], v[52:53], v[34:35] op_sel_hi:[0,1,1]
	v_pk_add_f32 v[34:35], v[124:125], v[34:35]
	ds_read_b128 v[50:53], v143 offset:12320
	ds_read_b128 v[118:121], v143 offset:12336
	ds_read_b128 v[122:125], v143 offset:14368
	ds_read_b128 v[126:129], v143 offset:14384
	s_waitcnt lgkmcnt(3)
	v_mov_b32_e32 v38, v50
	s_waitcnt lgkmcnt(1)
	v_mov_b32_e32 v39, v122
	v_mov_b32_e32 v122, v51
	v_pk_mul_f32 v[50:51], v[62:63], v[122:123] op_sel_hi:[0,1]
	v_pk_fma_f32 v[38:39], v[30:31], v[38:39], v[50:51] op_sel_hi:[0,1,1]
	v_mov_b32_e32 v50, v52
	v_mov_b32_e32 v51, v124
	v_pk_fma_f32 v[38:39], v[64:65], v[50:51], v[38:39] op_sel_hi:[0,1,1]
	v_mov_b32_e32 v124, v53
	v_pk_fma_f32 v[38:39], v[66:67], v[124:125], v[38:39] op_sel_hi:[0,1,1]
	v_mov_b32_e32 v50, v118
	s_waitcnt lgkmcnt(0)
	v_mov_b32_e32 v51, v126
	v_pk_fma_f32 v[38:39], v[70:71], v[50:51], v[38:39] op_sel_hi:[0,1,1]
	v_mov_b32_e32 v126, v119
	v_pk_fma_f32 v[38:39], v[72:73], v[126:127], v[38:39] op_sel_hi:[0,1,1]
	v_mov_b32_e32 v50, v120
	v_mov_b32_e32 v51, v128
	v_pk_fma_f32 v[38:39], v[74:75], v[50:51], v[38:39] op_sel_hi:[0,1,1]
	v_mov_b32_e32 v128, v121
	v_pk_fma_f32 v[38:39], v[76:77], v[128:129], v[38:39] op_sel_hi:[0,1,1]
	v_pk_add_f32 v[38:39], v[80:81], v[38:39]
	ds_read_b128 v[50:53], v143 offset:28688
	ds_read_b128 v[78:81], v143 offset:30736
	s_waitcnt lgkmcnt(1)
	v_mov_b32_e32 v28, v50
	s_waitcnt lgkmcnt(0)
	v_mov_b32_e32 v29, v78
	v_pk_fma_f32 v[24:25], v[136:137], v[28:29], v[24:25] op_sel_hi:[0,1,1]
	v_mov_b32_e32 v78, v51
	v_pk_fma_f32 v[24:25], v[138:139], v[78:79], v[24:25] op_sel_hi:[0,1,1]
	v_mov_b32_e32 v28, v52
	v_mov_b32_e32 v29, v80
	v_pk_fma_f32 v[24:25], v[140:141], v[28:29], v[24:25] op_sel_hi:[0,1,1]
	v_mov_b32_e32 v80, v53
	v_pk_fma_f32 v[24:25], v[142:143], v[80:81], v[24:25] op_sel_hi:[0,1,1]
	v_pk_add_f32 v[24:25], v[116:117], v[24:25]
	ds_read_b128 v[50:53], v143 offset:16416
	ds_read_b128 v[58:61], v143 offset:16432
	ds_read_b128 v[78:81], v143 offset:18464
	ds_read_b128 v[116:119], v143 offset:18480
	s_waitcnt lgkmcnt(3)
	v_mov_b32_e32 v28, v50
	s_waitcnt lgkmcnt(1)
	v_mov_b32_e32 v29, v78
	v_mov_b32_e32 v78, v51
	v_pk_mul_f32 v[50:51], v[62:63], v[78:79] op_sel_hi:[0,1]
	v_pk_fma_f32 v[28:29], v[30:31], v[28:29], v[50:51] op_sel_hi:[0,1,1]
	v_mov_b32_e32 v50, v52
	v_mov_b32_e32 v51, v80
	v_pk_fma_f32 v[28:29], v[64:65], v[50:51], v[28:29] op_sel_hi:[0,1,1]
	v_mov_b32_e32 v80, v53
	v_pk_fma_f32 v[28:29], v[66:67], v[80:81], v[28:29] op_sel_hi:[0,1,1]
	v_mov_b32_e32 v50, v58
	s_waitcnt lgkmcnt(0)
	v_mov_b32_e32 v51, v116
	v_pk_fma_f32 v[28:29], v[70:71], v[50:51], v[28:29] op_sel_hi:[0,1,1]
	v_mov_b32_e32 v116, v59
	v_pk_fma_f32 v[28:29], v[72:73], v[116:117], v[28:29] op_sel_hi:[0,1,1]
	v_mov_b32_e32 v50, v60
	v_mov_b32_e32 v51, v118
	v_pk_fma_f32 v[28:29], v[74:75], v[50:51], v[28:29] op_sel_hi:[0,1,1]
	v_mov_b32_e32 v118, v61
	v_pk_fma_f32 v[28:29], v[76:77], v[118:119], v[28:29] op_sel_hi:[0,1,1]
	v_pk_add_f32 v[28:29], v[56:57], v[28:29]
	ds_read_b128 v[50:53], v143 offset:20512
	ds_read_b128 v[54:57], v143 offset:32784
	ds_read_b128 v[58:61], v143 offset:34832
	s_waitcnt lgkmcnt(1)
	v_mov_b32_e32 v14, v54
	s_waitcnt lgkmcnt(0)
	v_mov_b32_e32 v15, v58
	v_pk_fma_f32 v[10:11], v[136:137], v[14:15], v[10:11] op_sel_hi:[0,1,1]
	v_mov_b32_e32 v58, v55
	v_pk_fma_f32 v[10:11], v[138:139], v[58:59], v[10:11] op_sel_hi:[0,1,1]
	v_mov_b32_e32 v14, v56
	v_mov_b32_e32 v15, v60
	v_pk_fma_f32 v[10:11], v[140:141], v[14:15], v[10:11] op_sel_hi:[0,1,1]
	v_mov_b32_e32 v60, v57
	v_pk_fma_f32 v[10:11], v[142:143], v[60:61], v[10:11] op_sel_hi:[0,1,1]
	ds_read_b128 v[54:57], v143 offset:20528
	ds_read_b128 v[58:61], v143 offset:22560
	ds_read_b128 v[78:81], v143 offset:22576
	v_pk_add_f32 v[36:37], v[112:113], v[10:11]
	v_mov_b32_e32 v10, v50
	s_waitcnt lgkmcnt(1)
	v_mov_b32_e32 v11, v58
	v_mov_b32_e32 v58, v51
	v_pk_mul_f32 v[14:15], v[62:63], v[58:59] op_sel_hi:[0,1]
	v_pk_fma_f32 v[10:11], v[30:31], v[10:11], v[14:15] op_sel_hi:[0,1,1]
	v_mov_b32_e32 v14, v52
	v_mov_b32_e32 v15, v60
	v_pk_fma_f32 v[10:11], v[64:65], v[14:15], v[10:11] op_sel_hi:[0,1,1]
	v_mov_b32_e32 v60, v53
	v_pk_fma_f32 v[10:11], v[66:67], v[60:61], v[10:11] op_sel_hi:[0,1,1]
	v_mov_b32_e32 v14, v54
	s_waitcnt lgkmcnt(0)
	v_mov_b32_e32 v15, v78
	v_pk_fma_f32 v[10:11], v[70:71], v[14:15], v[10:11] op_sel_hi:[0,1,1]
	v_mov_b32_e32 v78, v55
	v_pk_fma_f32 v[10:11], v[72:73], v[78:79], v[10:11] op_sel_hi:[0,1,1]
	v_mov_b32_e32 v14, v56
	v_mov_b32_e32 v15, v80
	v_pk_fma_f32 v[10:11], v[74:75], v[14:15], v[10:11] op_sel_hi:[0,1,1]
	v_mov_b32_e32 v80, v57
	v_pk_fma_f32 v[10:11], v[76:77], v[80:81], v[10:11] op_sel_hi:[0,1,1]
	ds_read_b128 v[50:53], v143 offset:24608
	ds_read_b128 v[54:57], v143 offset:24624
	ds_read_b128 v[58:61], v143 offset:36880
	ds_read_b128 v[78:81], v143 offset:38928
	v_pk_add_f32 v[10:11], v[44:45], v[10:11]
	s_waitcnt lgkmcnt(3)
; DI void phase_setup(const Params& p, char* lds) {
;     ...
;         for (int k8 = 0; k8 < 32; k8 += 8) {
;           float w[8];
; #pragma unroll
;           for (int u = 0; u < 8; ++u) w[u] = wp[(size_t)(k8 + u) * 3072];
; #pragma unroll
;           for (int bi = 0; bi < 24; ++bi) {
;             const float4 c0 = *(const float4*)(cs + bi * 512 + kp * 32 + k8), c1 = *(const float4*)(cs + bi * 512 + kp * 32 + k8 + 4);
;             acc[bi] += c0.x * w[0] + c0.y * w[1] + c0.z * w[2] + c0.w * w[3] + c1.x * w[4] + c1.y * w[5] + c1.z * w[6] + c1.w * w[7];
;           }
	v_mov_b32_e32 v8, v50
	s_waitcnt lgkmcnt(1)
	v_mov_b32_e32 v6, v58
	s_waitcnt lgkmcnt(0)
	v_mov_b32_e32 v7, v78
	v_pk_fma_f32 v[4:5], v[136:137], v[6:7], v[4:5] op_sel_hi:[0,1,1]
	v_mov_b32_e32 v78, v59
	v_pk_fma_f32 v[4:5], v[138:139], v[78:79], v[4:5] op_sel_hi:[0,1,1]
	v_mov_b32_e32 v6, v60
	v_mov_b32_e32 v7, v80
	v_pk_fma_f32 v[4:5], v[140:141], v[6:7], v[4:5] op_sel_hi:[0,1,1]
	v_mov_b32_e32 v80, v61
	v_pk_fma_f32 v[4:5], v[142:143], v[80:81], v[4:5] op_sel_hi:[0,1,1]
	v_pk_add_f32 v[58:59], v[114:115], v[4:5]
	ds_read_b128 v[4:7], v143 offset:26656
	ds_read_b128 v[12:15], v143 offset:26672
	s_waitcnt lgkmcnt(1)
	v_mov_b32_e32 v9, v4
	v_mov_b32_e32 v4, v51
	v_pk_mul_f32 v[4:5], v[62:63], v[4:5] op_sel_hi:[0,1]
	v_pk_fma_f32 v[4:5], v[30:31], v[8:9], v[4:5] op_sel_hi:[0,1,1]
	v_mov_b32_e32 v8, v52
	v_mov_b32_e32 v9, v6
	v_pk_fma_f32 v[4:5], v[64:65], v[8:9], v[4:5] op_sel_hi:[0,1,1]
	v_mov_b32_e32 v6, v53
	v_pk_fma_f32 v[4:5], v[66:67], v[6:7], v[4:5] op_sel_hi:[0,1,1]
	v_mov_b32_e32 v6, v54
	s_waitcnt lgkmcnt(0)
	v_mov_b32_e32 v7, v12
	v_pk_fma_f32 v[4:5], v[70:71], v[6:7], v[4:5] op_sel_hi:[0,1,1]
	v_mov_b32_e32 v12, v55
	v_pk_fma_f32 v[4:5], v[72:73], v[12:13], v[4:5] op_sel_hi:[0,1,1]
	v_mov_b32_e32 v6, v56
	v_mov_b32_e32 v7, v14
	v_pk_fma_f32 v[4:5], v[74:75], v[6:7], v[4:5] op_sel_hi:[0,1,1]
	v_mov_b32_e32 v14, v57
	v_pk_fma_f32 v[4:5], v[76:77], v[14:15], v[4:5] op_sel_hi:[0,1,1]
	v_pk_add_f32 v[4:5], v[48:49], v[4:5]
	ds_read_b128 v[6:9], v143 offset:28704
	ds_read_b128 v[12:15], v143 offset:28720
	ds_read_b128 v[48:51], v143 offset:30752
	ds_read_b128 v[52:55], v143 offset:30768
	s_waitcnt lgkmcnt(3)
	v_mov_b32_e32 v26, v6
	s_waitcnt lgkmcnt(1)
	v_mov_b32_e32 v27, v48
	v_mov_b32_e32 v48, v7
	v_pk_mul_f32 v[6:7], v[62:63], v[48:49] op_sel_hi:[0,1]
	v_pk_fma_f32 v[6:7], v[30:31], v[26:27], v[6:7] op_sel_hi:[0,1,1]
	v_mov_b32_e32 v26, v8
	v_mov_b32_e32 v27, v50
	v_pk_fma_f32 v[6:7], v[64:65], v[26:27], v[6:7] op_sel_hi:[0,1,1]
	v_mov_b32_e32 v50, v9
	v_pk_fma_f32 v[6:7], v[66:67], v[50:51], v[6:7] op_sel_hi:[0,1,1]
	v_mov_b32_e32 v8, v12
	s_waitcnt lgkmcnt(0)
	v_mov_b32_e32 v9, v52
	v_pk_fma_f32 v[6:7], v[70:71], v[8:9], v[6:7] op_sel_hi:[0,1,1]
	v_mov_b32_e32 v52, v13
	v_pk_fma_f32 v[6:7], v[72:73], v[52:53], v[6:7] op_sel_hi:[0,1,1]
	v_mov_b32_e32 v8, v14
	v_mov_b32_e32 v9, v54
	v_pk_fma_f32 v[6:7], v[74:75], v[8:9], v[6:7] op_sel_hi:[0,1,1]
	v_mov_b32_e32 v54, v15
	v_mov_b32_e32 v8, v2
	v_mov_b32_e32 v9, v18
	v_pk_fma_f32 v[6:7], v[76:77], v[54:55], v[6:7] op_sel_hi:[0,1,1]
	v_pk_fma_f32 v[0:1], v[132:133], v[8:9], v[0:1] op_sel_hi:[0,1,1]
	v_mov_b32_e32 v18, v3
	v_pk_add_f32 v[6:7], v[24:25], v[6:7]
	ds_read_b128 v[12:15], v143 offset:32800
	ds_read_b128 v[24:27], v143 offset:32816
	ds_read_b128 v[48:51], v143 offset:40976
	v_pk_fma_f32 v[8:9], v[134:135], v[18:19], v[0:1] op_sel_hi:[0,1,1]
	ds_read_b128 v[0:3], v143 offset:43024
	s_waitcnt lgkmcnt(1)
	v_mov_b32_e32 v18, v48
	s_waitcnt lgkmcnt(0)
	v_mov_b32_e32 v19, v0
	v_pk_fma_f32 v[8:9], v[136:137], v[18:19], v[8:9] op_sel_hi:[0,1,1]
	v_mov_b32_e32 v0, v49
	v_pk_fma_f32 v[0:1], v[138:139], v[0:1], v[8:9] op_sel_hi:[0,1,1]
	v_mov_b32_e32 v8, v50
	v_mov_b32_e32 v9, v2
	v_pk_fma_f32 v[0:1], v[140:141], v[8:9], v[0:1] op_sel_hi:[0,1,1]
	v_mov_b32_e32 v2, v51
	v_pk_fma_f32 v[0:1], v[142:143], v[2:3], v[0:1] op_sel_hi:[0,1,1]
	v_pk_add_f32 v[8:9], v[110:111], v[0:1]
	ds_read_b128 v[0:3], v143 offset:34848
	ds_read_b128 v[42:45], v143 offset:34864
	v_mov_b32_e32 v18, v12
	v_mov_b32_e32 v12, v14
	s_waitcnt lgkmcnt(1)
	v_mov_b32_e32 v19, v0
	v_mov_b32_e32 v0, v13
	v_pk_mul_f32 v[0:1], v[62:63], v[0:1] op_sel_hi:[0,1]
	v_pk_fma_f32 v[0:1], v[30:31], v[18:19], v[0:1] op_sel_hi:[0,1,1]
	v_mov_b32_e32 v13, v2
	v_pk_fma_f32 v[0:1], v[64:65], v[12:13], v[0:1] op_sel_hi:[0,1,1]
	v_mov_b32_e32 v2, v15
	v_pk_fma_f32 v[0:1], v[66:67], v[2:3], v[0:1] op_sel_hi:[0,1,1]
	v_mov_b32_e32 v2, v24
	s_waitcnt lgkmcnt(0)
	v_mov_b32_e32 v3, v42
	v_pk_fma_f32 v[0:1], v[70:71], v[2:3], v[0:1] op_sel_hi:[0,1,1]
	v_mov_b32_e32 v42, v25
	v_pk_fma_f32 v[0:1], v[72:73], v[42:43], v[0:1] op_sel_hi:[0,1,1]
	v_mov_b32_e32 v2, v26
	v_mov_b32_e32 v3, v44
	v_pk_fma_f32 v[0:1], v[74:75], v[2:3], v[0:1] op_sel_hi:[0,1,1]
	v_mov_b32_e32 v44, v27
	v_pk_fma_f32 v[0:1], v[76:77], v[44:45], v[0:1] op_sel_hi:[0,1,1]
	ds_read_b128 v[12:15], v143 offset:36896
	ds_read_b128 v[24:27], v143 offset:36912
	ds_read_b128 v[42:45], v143 offset:38944
	ds_read_b128 v[48:51], v143 offset:38960
	v_mov_b32_e32 v18, v22
	s_waitcnt lgkmcnt(3)
	v_mov_b32_e32 v2, v12
	v_mov_b32_e32 v19, v32
	s_waitcnt lgkmcnt(1)
	v_mov_b32_e32 v3, v42
	v_mov_b32_e32 v42, v13
	v_pk_mul_f32 v[12:13], v[62:63], v[42:43] op_sel_hi:[0,1]
	v_pk_fma_f32 v[2:3], v[30:31], v[2:3], v[12:13] op_sel_hi:[0,1,1]
	v_mov_b32_e32 v12, v14
	v_mov_b32_e32 v13, v44
	v_pk_fma_f32 v[2:3], v[64:65], v[12:13], v[2:3] op_sel_hi:[0,1,1]
	v_mov_b32_e32 v44, v15
	v_pk_fma_f32 v[2:3], v[66:67], v[44:45], v[2:3] op_sel_hi:[0,1,1]
	v_mov_b32_e32 v12, v24
	s_waitcnt lgkmcnt(0)
	v_mov_b32_e32 v13, v48
	v_pk_fma_f32 v[2:3], v[70:71], v[12:13], v[2:3] op_sel_hi:[0,1,1]
	v_mov_b32_e32 v48, v25
	v_pk_fma_f32 v[2:3], v[72:73], v[48:49], v[2:3] op_sel_hi:[0,1,1]
	v_mov_b32_e32 v12, v26
	v_mov_b32_e32 v13, v50
	v_pk_fma_f32 v[2:3], v[74:75], v[12:13], v[2:3] op_sel_hi:[0,1,1]
	v_mov_b32_e32 v50, v27
	v_pk_fma_f32 v[2:3], v[76:77], v[50:51], v[2:3] op_sel_hi:[0,1,1]
	ds_read_b128 v[12:15], v143 offset:40992
	ds_read_b128 v[24:27], v143 offset:41008
	ds_read_b128 v[42:45], v143 offset:45072
	ds_read_b128 v[48:51], v143 offset:47120
	v_pk_fma_f32 v[16:17], v[132:133], v[18:19], v[16:17] op_sel_hi:[0,1,1]
	v_mov_b32_e32 v32, v23
	v_pk_fma_f32 v[16:17], v[134:135], v[32:33], v[16:17] op_sel_hi:[0,1,1]
	s_waitcnt lgkmcnt(1)
; DI void phase_setup(const Params& p, char* lds) {
;     ...
;         for (int k8 = 0; k8 < 32; k8 += 8) {
;           float w[8];
; #pragma unroll
;           for (int u = 0; u < 8; ++u) w[u] = wp[(size_t)(k8 + u) * 3072];
; #pragma unroll
;           for (int bi = 0; bi < 24; ++bi) {
;             const float4 c0 = *(const float4*)(cs + bi * 512 + kp * 32 + k8), c1 = *(const float4*)(cs + bi * 512 + kp * 32 + k8 + 4);
;             acc[bi] += c0.x * w[0] + c0.y * w[1] + c0.z * w[2] + c0.w * w[3] + c1.x * w[4] + c1.y * w[5] + c1.z * w[6] + c1.w * w[7];
;           }
	v_mov_b32_e32 v18, v42
	s_waitcnt lgkmcnt(0)
	v_mov_b32_e32 v19, v48
	v_pk_fma_f32 v[16:17], v[136:137], v[18:19], v[16:17] op_sel_hi:[0,1,1]
	v_mov_b32_e32 v48, v43
	v_pk_fma_f32 v[16:17], v[138:139], v[48:49], v[16:17] op_sel_hi:[0,1,1]
	v_mov_b32_e32 v18, v44
	v_mov_b32_e32 v19, v50
	v_pk_fma_f32 v[16:17], v[140:141], v[18:19], v[16:17] op_sel_hi:[0,1,1]
	v_mov_b32_e32 v50, v45
	v_pk_fma_f32 v[16:17], v[142:143], v[50:51], v[16:17] op_sel_hi:[0,1,1]
	v_pk_add_f32 v[32:33], v[108:109], v[16:17]
	ds_read_b128 v[16:19], v143 offset:43040
	ds_read_b128 v[20:23], v143 offset:43056
	v_pk_add_f32 v[0:1], v[36:37], v[0:1]
	v_mov_b32_e32 v36, v12
	v_pk_add_f32 v[2:3], v[58:59], v[2:3]
	s_waitcnt lgkmcnt(1)
	v_mov_b32_e32 v37, v16
	v_mov_b32_e32 v16, v13
	v_pk_mul_f32 v[12:13], v[62:63], v[16:17] op_sel_hi:[0,1]
	v_pk_fma_f32 v[12:13], v[30:31], v[36:37], v[12:13] op_sel_hi:[0,1,1]
	v_mov_b32_e32 v16, v14
	v_mov_b32_e32 v17, v18
	v_pk_fma_f32 v[12:13], v[64:65], v[16:17], v[12:13] op_sel_hi:[0,1,1]
	v_mov_b32_e32 v18, v15
	v_pk_fma_f32 v[12:13], v[66:67], v[18:19], v[12:13] op_sel_hi:[0,1,1]
	v_mov_b32_e32 v14, v24
	s_waitcnt lgkmcnt(0)
	v_mov_b32_e32 v15, v20
	v_pk_fma_f32 v[12:13], v[70:71], v[14:15], v[12:13] op_sel_hi:[0,1,1]
	v_mov_b32_e32 v20, v25
	v_pk_fma_f32 v[12:13], v[72:73], v[20:21], v[12:13] op_sel_hi:[0,1,1]
	v_mov_b32_e32 v14, v26
	v_mov_b32_e32 v15, v22
	v_pk_fma_f32 v[12:13], v[74:75], v[14:15], v[12:13] op_sel_hi:[0,1,1]
	v_mov_b32_e32 v22, v27
	v_pk_fma_f32 v[12:13], v[76:77], v[22:23], v[12:13] op_sel_hi:[0,1,1]
	v_pk_add_f32 v[26:27], v[8:9], v[12:13]
	ds_read_b128 v[12:15], v143 offset:45088
	ds_read_b128 v[16:19], v143 offset:45104
	ds_read_b128 v[20:23], v143 offset:47136
	ds_read_b128 v[42:45], v143 offset:47152
	s_waitcnt lgkmcnt(3)
	v_mov_b32_e32 v8, v12
	s_waitcnt lgkmcnt(1)
	v_mov_b32_e32 v9, v20
	v_mov_b32_e32 v20, v13
	v_pk_mul_f32 v[12:13], v[62:63], v[20:21] op_sel_hi:[0,1]
	v_pk_fma_f32 v[8:9], v[30:31], v[8:9], v[12:13] op_sel_hi:[0,1,1]
	v_mov_b32_e32 v12, v14
	v_mov_b32_e32 v13, v22
	v_pk_fma_f32 v[8:9], v[64:65], v[12:13], v[8:9] op_sel_hi:[0,1,1]
	v_mov_b32_e32 v22, v15
	v_pk_fma_f32 v[8:9], v[66:67], v[22:23], v[8:9] op_sel_hi:[0,1,1]
	v_mov_b32_e32 v12, v16
	s_waitcnt lgkmcnt(0)
	v_mov_b32_e32 v13, v42
	v_pk_fma_f32 v[8:9], v[70:71], v[12:13], v[8:9] op_sel_hi:[0,1,1]
	v_mov_b32_e32 v42, v17
	v_pk_fma_f32 v[8:9], v[72:73], v[42:43], v[8:9] op_sel_hi:[0,1,1]
	v_mov_b32_e32 v12, v18
	v_mov_b32_e32 v13, v44
	v_pk_fma_f32 v[8:9], v[74:75], v[12:13], v[8:9] op_sel_hi:[0,1,1]
	v_mov_b32_e32 v44, v19
	v_pk_fma_f32 v[8:9], v[76:77], v[44:45], v[8:9] op_sel_hi:[0,1,1]
	v_pk_add_f32 v[30:31], v[32:33], v[8:9]
	v_add_co_u32_e32 v8, vcc, s0, v106
	s_mov_b32 s0, 0x33000
	s_nop 0
	v_addc_co_u32_e32 v9, vcc, 0, v107, vcc
	s_waitcnt vmcnt(8)
	v_mov_b32_e32 v32, v226
	v_add_co_u32_e32 v8, vcc, s0, v106
	s_mov_b32 s0, 0x36000
	s_nop 0
	v_addc_co_u32_e32 v9, vcc, 0, v107, vcc
	v_mov_b32_e32 v36, v227
	v_add_co_u32_e32 v8, vcc, s0, v106
	s_mov_b32 s0, 0x39000
	s_nop 0
	v_addc_co_u32_e32 v9, vcc, 0, v107, vcc
	v_mov_b32_e32 v42, v228
	v_add_co_u32_e32 v8, vcc, s0, v106
	s_mov_b32 s0, 0x3c000
	s_nop 0
	v_addc_co_u32_e32 v9, vcc, 0, v107, vcc
	v_mov_b32_e32 v44, v229
	v_add_co_u32_e32 v8, vcc, s0, v106
	s_mov_b32 s0, 0x3f000
	s_nop 0
	v_addc_co_u32_e32 v9, vcc, 0, v107, vcc
	v_mov_b32_e32 v48, v230
	v_add_co_u32_e32 v8, vcc, s0, v106
	s_mov_b32 s0, 0x42000
	s_nop 0
	v_addc_co_u32_e32 v9, vcc, 0, v107, vcc
	v_mov_b32_e32 v50, v231
	v_add_co_u32_e32 v8, vcc, s0, v106
	s_mov_b32 s0, 0x45000
	s_nop 0
	v_addc_co_u32_e32 v9, vcc, 0, v107, vcc
	v_mov_b32_e32 v52, v232
	v_add_co_u32_e32 v8, vcc, s0, v106
	s_mov_b32 s0, 0x48000
	s_nop 0
	v_addc_co_u32_e32 v9, vcc, 0, v107, vcc
	v_mov_b32_e32 v54, v233
	ds_read_b128 v[12:15], v143 offset:64
	ds_read_b128 v[16:19], v143 offset:80
	ds_read_b128 v[20:23], v143 offset:2112
	ds_read_b128 v[56:59], v143 offset:2128
	s_waitcnt lgkmcnt(3)
	v_mov_b32_e32 v8, v12
	s_waitcnt lgkmcnt(1)
	v_mov_b32_e32 v9, v20
	v_mov_b32_e32 v20, v13
	s_waitcnt vmcnt(14)
	v_pk_mul_f32 v[12:13], v[36:37], v[20:21] op_sel_hi:[0,1]
	v_pk_fma_f32 v[8:9], v[32:33], v[8:9], v[12:13] op_sel_hi:[0,1,1]
	v_mov_b32_e32 v12, v14
	v_mov_b32_e32 v13, v22
	v_mov_b32_e32 v22, v15
	s_waitcnt vmcnt(13)
	v_pk_fma_f32 v[8:9], v[42:43], v[12:13], v[8:9] op_sel_hi:[0,1,1]
	v_mov_b32_e32 v12, v16
	s_waitcnt lgkmcnt(0)
	v_mov_b32_e32 v13, v56
	v_mov_b32_e32 v56, v17
	s_waitcnt vmcnt(12)
	v_pk_fma_f32 v[8:9], v[44:45], v[22:23], v[8:9] op_sel_hi:[0,1,1]
	s_waitcnt vmcnt(11)
	v_pk_fma_f32 v[8:9], v[48:49], v[12:13], v[8:9] op_sel_hi:[0,1,1]
	v_mov_b32_e32 v12, v18
	v_mov_b32_e32 v13, v58
	v_mov_b32_e32 v58, v19
	s_waitcnt vmcnt(10)
	v_pk_fma_f32 v[8:9], v[50:51], v[56:57], v[8:9] op_sel_hi:[0,1,1]
	s_waitcnt vmcnt(9)
	v_pk_fma_f32 v[8:9], v[52:53], v[12:13], v[8:9] op_sel_hi:[0,1,1]
	s_waitcnt vmcnt(8)
	v_pk_fma_f32 v[8:9], v[54:55], v[58:59], v[8:9] op_sel_hi:[0,1,1]
	ds_read_b128 v[12:15], v143 offset:4160
	ds_read_b128 v[16:19], v143 offset:4176
	ds_read_b128 v[20:23], v143 offset:6208
	ds_read_b128 v[56:59], v143 offset:6224
	v_pk_add_f32 v[24:25], v[46:47], v[8:9]
	s_waitcnt lgkmcnt(3)
	v_mov_b32_e32 v8, v12
	s_waitcnt lgkmcnt(1)
	v_mov_b32_e32 v9, v20
	v_mov_b32_e32 v20, v13
	v_pk_mul_f32 v[12:13], v[36:37], v[20:21] op_sel_hi:[0,1]
	v_pk_fma_f32 v[8:9], v[32:33], v[8:9], v[12:13] op_sel_hi:[0,1,1]
	v_mov_b32_e32 v12, v14
	v_mov_b32_e32 v13, v22
	v_pk_fma_f32 v[8:9], v[42:43], v[12:13], v[8:9] op_sel_hi:[0,1,1]
	v_mov_b32_e32 v22, v15
	v_pk_fma_f32 v[8:9], v[44:45], v[22:23], v[8:9] op_sel_hi:[0,1,1]
	v_mov_b32_e32 v12, v16
	s_waitcnt lgkmcnt(0)
; DI void phase_setup(const Params& p, char* lds) {
;     ...
;         for (int k8 = 0; k8 < 32; k8 += 8) {
;           float w[8];
; #pragma unroll
;           for (int u = 0; u < 8; ++u) w[u] = wp[(size_t)(k8 + u) * 3072];
; #pragma unroll
;           for (int bi = 0; bi < 24; ++bi) {
;             const float4 c0 = *(const float4*)(cs + bi * 512 + kp * 32 + k8), c1 = *(const float4*)(cs + bi * 512 + kp * 32 + k8 + 4);
;             acc[bi] += c0.x * w[0] + c0.y * w[1] + c0.z * w[2] + c0.w * w[3] + c1.x * w[4] + c1.y * w[5] + c1.z * w[6] + c1.w * w[7];
;           }
	v_mov_b32_e32 v13, v56
	v_pk_fma_f32 v[8:9], v[48:49], v[12:13], v[8:9] op_sel_hi:[0,1,1]
	v_mov_b32_e32 v56, v17
	v_pk_fma_f32 v[8:9], v[50:51], v[56:57], v[8:9] op_sel_hi:[0,1,1]
	v_mov_b32_e32 v12, v18
	v_mov_b32_e32 v13, v58
	v_pk_fma_f32 v[8:9], v[52:53], v[12:13], v[8:9] op_sel_hi:[0,1,1]
	v_mov_b32_e32 v58, v19
	v_pk_fma_f32 v[8:9], v[54:55], v[58:59], v[8:9] op_sel_hi:[0,1,1]
	ds_read_b128 v[12:15], v143 offset:8256
	ds_read_b128 v[16:19], v143 offset:8272
	ds_read_b128 v[56:59], v143 offset:10304
	ds_read_b128 v[60:63], v143 offset:10320
	v_pk_add_f32 v[22:23], v[40:41], v[8:9]
	s_waitcnt lgkmcnt(3)
	v_mov_b32_e32 v8, v12
	s_waitcnt lgkmcnt(1)
	v_mov_b32_e32 v9, v56
	v_mov_b32_e32 v56, v13
	v_pk_mul_f32 v[12:13], v[36:37], v[56:57] op_sel_hi:[0,1]
	v_pk_fma_f32 v[8:9], v[32:33], v[8:9], v[12:13] op_sel_hi:[0,1,1]
	v_mov_b32_e32 v12, v14
	v_mov_b32_e32 v13, v58
	v_pk_fma_f32 v[8:9], v[42:43], v[12:13], v[8:9] op_sel_hi:[0,1,1]
	v_mov_b32_e32 v58, v15
	v_pk_fma_f32 v[8:9], v[44:45], v[58:59], v[8:9] op_sel_hi:[0,1,1]
	v_mov_b32_e32 v12, v16
	s_waitcnt lgkmcnt(0)
	v_mov_b32_e32 v13, v60
	v_pk_fma_f32 v[8:9], v[48:49], v[12:13], v[8:9] op_sel_hi:[0,1,1]
	v_mov_b32_e32 v60, v17
	v_pk_fma_f32 v[8:9], v[50:51], v[60:61], v[8:9] op_sel_hi:[0,1,1]
	v_mov_b32_e32 v12, v18
	v_mov_b32_e32 v13, v62
	v_pk_fma_f32 v[8:9], v[52:53], v[12:13], v[8:9] op_sel_hi:[0,1,1]
	v_mov_b32_e32 v62, v19
	v_pk_fma_f32 v[8:9], v[54:55], v[62:63], v[8:9] op_sel_hi:[0,1,1]
	ds_read_b128 v[12:15], v143 offset:12352
	ds_read_b128 v[16:19], v143 offset:12368
	ds_read_b128 v[56:59], v143 offset:14400
	ds_read_b128 v[60:63], v143 offset:14416
	v_pk_add_f32 v[20:21], v[34:35], v[8:9]
	s_waitcnt lgkmcnt(3)
	v_mov_b32_e32 v8, v12
	s_waitcnt lgkmcnt(1)
	v_mov_b32_e32 v9, v56
	v_mov_b32_e32 v56, v13
	v_pk_mul_f32 v[12:13], v[36:37], v[56:57] op_sel_hi:[0,1]
	v_pk_fma_f32 v[8:9], v[32:33], v[8:9], v[12:13] op_sel_hi:[0,1,1]
	v_mov_b32_e32 v12, v14
	v_mov_b32_e32 v13, v58
	v_pk_fma_f32 v[8:9], v[42:43], v[12:13], v[8:9] op_sel_hi:[0,1,1]
	v_mov_b32_e32 v58, v15
	v_pk_fma_f32 v[8:9], v[44:45], v[58:59], v[8:9] op_sel_hi:[0,1,1]
	v_mov_b32_e32 v12, v16
	s_waitcnt lgkmcnt(0)
	v_mov_b32_e32 v13, v60
	v_pk_fma_f32 v[8:9], v[48:49], v[12:13], v[8:9] op_sel_hi:[0,1,1]
	v_mov_b32_e32 v60, v17
	v_pk_fma_f32 v[8:9], v[50:51], v[60:61], v[8:9] op_sel_hi:[0,1,1]
	v_mov_b32_e32 v12, v18
	v_mov_b32_e32 v13, v62
	v_pk_fma_f32 v[8:9], v[52:53], v[12:13], v[8:9] op_sel_hi:[0,1,1]
	v_mov_b32_e32 v62, v19
	v_pk_fma_f32 v[8:9], v[54:55], v[62:63], v[8:9] op_sel_hi:[0,1,1]
	v_pk_add_f32 v[18:19], v[38:39], v[8:9]
	ds_read_b128 v[12:15], v143 offset:16448
	ds_read_b128 v[38:41], v143 offset:16464
	ds_read_b128 v[56:59], v143 offset:18496
	ds_read_b128 v[60:63], v143 offset:18512
	s_waitcnt lgkmcnt(3)
	v_mov_b32_e32 v8, v12
	s_waitcnt lgkmcnt(1)
	v_mov_b32_e32 v9, v56
	v_mov_b32_e32 v56, v13
	v_pk_mul_f32 v[12:13], v[36:37], v[56:57] op_sel_hi:[0,1]
	v_pk_fma_f32 v[8:9], v[32:33], v[8:9], v[12:13] op_sel_hi:[0,1,1]
	v_mov_b32_e32 v12, v14
	v_mov_b32_e32 v13, v58
	v_pk_fma_f32 v[8:9], v[42:43], v[12:13], v[8:9] op_sel_hi:[0,1,1]
	v_mov_b32_e32 v58, v15
	v_pk_fma_f32 v[8:9], v[44:45], v[58:59], v[8:9] op_sel_hi:[0,1,1]
	v_mov_b32_e32 v12, v38
	s_waitcnt lgkmcnt(0)
	v_mov_b32_e32 v13, v60
	v_pk_fma_f32 v[8:9], v[48:49], v[12:13], v[8:9] op_sel_hi:[0,1,1]
	v_mov_b32_e32 v60, v39
	v_pk_fma_f32 v[8:9], v[50:51], v[60:61], v[8:9] op_sel_hi:[0,1,1]
	v_mov_b32_e32 v12, v40
	v_mov_b32_e32 v13, v62
	v_pk_fma_f32 v[8:9], v[52:53], v[12:13], v[8:9] op_sel_hi:[0,1,1]
	v_mov_b32_e32 v62, v41
	v_pk_fma_f32 v[8:9], v[54:55], v[62:63], v[8:9] op_sel_hi:[0,1,1]
	ds_read_b128 v[12:15], v143 offset:20544
	ds_read_b128 v[38:41], v143 offset:20560
	ds_read_b128 v[56:59], v143 offset:22592
	ds_read_b128 v[60:63], v143 offset:22608
	v_pk_add_f32 v[16:17], v[28:29], v[8:9]
	s_waitcnt lgkmcnt(3)
	v_mov_b32_e32 v8, v12
	s_waitcnt lgkmcnt(1)
	v_mov_b32_e32 v9, v56
	v_mov_b32_e32 v56, v13
	v_pk_mul_f32 v[12:13], v[36:37], v[56:57] op_sel_hi:[0,1]
	v_pk_fma_f32 v[8:9], v[32:33], v[8:9], v[12:13] op_sel_hi:[0,1,1]
	v_mov_b32_e32 v12, v14
	v_mov_b32_e32 v13, v58
	v_pk_fma_f32 v[8:9], v[42:43], v[12:13], v[8:9] op_sel_hi:[0,1,1]
	v_mov_b32_e32 v58, v15
	v_pk_fma_f32 v[8:9], v[44:45], v[58:59], v[8:9] op_sel_hi:[0,1,1]
	v_mov_b32_e32 v12, v38
	s_waitcnt lgkmcnt(0)
	v_mov_b32_e32 v13, v60
	v_pk_fma_f32 v[8:9], v[48:49], v[12:13], v[8:9] op_sel_hi:[0,1,1]
	v_mov_b32_e32 v60, v39
	v_pk_fma_f32 v[8:9], v[50:51], v[60:61], v[8:9] op_sel_hi:[0,1,1]
	v_mov_b32_e32 v12, v40
	v_mov_b32_e32 v13, v62
	v_pk_fma_f32 v[8:9], v[52:53], v[12:13], v[8:9] op_sel_hi:[0,1,1]
	v_mov_b32_e32 v62, v41
	v_pk_fma_f32 v[8:9], v[54:55], v[62:63], v[8:9] op_sel_hi:[0,1,1]
	v_pk_add_f32 v[14:15], v[10:11], v[8:9]
	ds_read_b128 v[8:11], v143 offset:24640
	ds_read_b128 v[38:41], v143 offset:24656
	ds_read_b128 v[56:59], v143 offset:26688
	ds_read_b128 v[60:63], v143 offset:26704
	s_waitcnt lgkmcnt(3)
	v_mov_b32_e32 v12, v8
	s_waitcnt lgkmcnt(1)
	v_mov_b32_e32 v13, v56
	v_mov_b32_e32 v56, v9
	v_pk_mul_f32 v[8:9], v[36:37], v[56:57] op_sel_hi:[0,1]
	v_pk_fma_f32 v[8:9], v[32:33], v[12:13], v[8:9] op_sel_hi:[0,1,1]
	v_mov_b32_e32 v12, v10
	v_mov_b32_e32 v13, v58
	v_pk_fma_f32 v[8:9], v[42:43], v[12:13], v[8:9] op_sel_hi:[0,1,1]
	v_mov_b32_e32 v58, v11
	v_pk_fma_f32 v[8:9], v[44:45], v[58:59], v[8:9] op_sel_hi:[0,1,1]
	v_mov_b32_e32 v10, v38
	s_waitcnt lgkmcnt(0)
; DI void phase_setup(const Params& p, char* lds) {
;     ...
;         for (int k8 = 0; k8 < 32; k8 += 8) {
;           float w[8];
; #pragma unroll
;           for (int u = 0; u < 8; ++u) w[u] = wp[(size_t)(k8 + u) * 3072];
; #pragma unroll
;           for (int bi = 0; bi < 24; ++bi) {
;             const float4 c0 = *(const float4*)(cs + bi * 512 + kp * 32 + k8), c1 = *(const float4*)(cs + bi * 512 + kp * 32 + k8 + 4);
;             acc[bi] += c0.x * w[0] + c0.y * w[1] + c0.z * w[2] + c0.w * w[3] + c1.x * w[4] + c1.y * w[5] + c1.z * w[6] + c1.w * w[7];
;           }
	v_mov_b32_e32 v11, v60
	v_pk_fma_f32 v[8:9], v[48:49], v[10:11], v[8:9] op_sel_hi:[0,1,1]
	v_mov_b32_e32 v60, v39
	v_pk_fma_f32 v[8:9], v[50:51], v[60:61], v[8:9] op_sel_hi:[0,1,1]
	v_mov_b32_e32 v10, v40
	v_mov_b32_e32 v11, v62
	v_pk_fma_f32 v[8:9], v[52:53], v[10:11], v[8:9] op_sel_hi:[0,1,1]
	v_mov_b32_e32 v62, v41
	v_pk_fma_f32 v[8:9], v[54:55], v[62:63], v[8:9] op_sel_hi:[0,1,1]
	v_pk_add_f32 v[12:13], v[4:5], v[8:9]
	ds_read_b128 v[8:11], v143 offset:28736
	ds_read_b128 v[38:41], v143 offset:28752
	ds_read_b128 v[56:59], v143 offset:30784
	ds_read_b128 v[60:63], v143 offset:30800
	s_waitcnt lgkmcnt(3)
	v_mov_b32_e32 v4, v8
	s_waitcnt lgkmcnt(1)
	v_mov_b32_e32 v5, v56
	v_mov_b32_e32 v56, v9
	v_pk_mul_f32 v[8:9], v[36:37], v[56:57] op_sel_hi:[0,1]
	v_pk_fma_f32 v[4:5], v[32:33], v[4:5], v[8:9] op_sel_hi:[0,1,1]
	v_mov_b32_e32 v8, v10
	v_mov_b32_e32 v9, v58
	v_pk_fma_f32 v[4:5], v[42:43], v[8:9], v[4:5] op_sel_hi:[0,1,1]
	v_mov_b32_e32 v58, v11
	v_pk_fma_f32 v[4:5], v[44:45], v[58:59], v[4:5] op_sel_hi:[0,1,1]
	v_mov_b32_e32 v8, v38
	s_waitcnt lgkmcnt(0)
	v_mov_b32_e32 v9, v60
	v_pk_fma_f32 v[4:5], v[48:49], v[8:9], v[4:5] op_sel_hi:[0,1,1]
	v_mov_b32_e32 v60, v39
	v_pk_fma_f32 v[4:5], v[50:51], v[60:61], v[4:5] op_sel_hi:[0,1,1]
	v_mov_b32_e32 v8, v40
	v_mov_b32_e32 v9, v62
	v_pk_fma_f32 v[4:5], v[52:53], v[8:9], v[4:5] op_sel_hi:[0,1,1]
	v_mov_b32_e32 v62, v41
	v_pk_fma_f32 v[4:5], v[54:55], v[62:63], v[4:5] op_sel_hi:[0,1,1]
	v_pk_add_f32 v[10:11], v[6:7], v[4:5]
	ds_read_b128 v[4:7], v143 offset:32832
	ds_read_b128 v[38:41], v143 offset:32848
	ds_read_b128 v[56:59], v143 offset:34880
	ds_read_b128 v[60:63], v143 offset:34896
	s_waitcnt lgkmcnt(3)
	v_mov_b32_e32 v8, v4
	s_waitcnt lgkmcnt(1)
	v_mov_b32_e32 v9, v56
	v_mov_b32_e32 v56, v5
	v_pk_mul_f32 v[4:5], v[36:37], v[56:57] op_sel_hi:[0,1]
	v_pk_fma_f32 v[4:5], v[32:33], v[8:9], v[4:5] op_sel_hi:[0,1,1]
	v_mov_b32_e32 v8, v6
	v_mov_b32_e32 v9, v58
	v_pk_fma_f32 v[4:5], v[42:43], v[8:9], v[4:5] op_sel_hi:[0,1,1]
	v_mov_b32_e32 v58, v7
	v_pk_fma_f32 v[4:5], v[44:45], v[58:59], v[4:5] op_sel_hi:[0,1,1]
	v_mov_b32_e32 v6, v38
	s_waitcnt lgkmcnt(0)
	v_mov_b32_e32 v7, v60
	v_pk_fma_f32 v[4:5], v[48:49], v[6:7], v[4:5] op_sel_hi:[0,1,1]
	v_mov_b32_e32 v60, v39
	v_pk_fma_f32 v[4:5], v[50:51], v[60:61], v[4:5] op_sel_hi:[0,1,1]
	v_mov_b32_e32 v6, v40
	v_mov_b32_e32 v7, v62
	v_pk_fma_f32 v[4:5], v[52:53], v[6:7], v[4:5] op_sel_hi:[0,1,1]
	v_mov_b32_e32 v62, v41
	v_pk_fma_f32 v[4:5], v[54:55], v[62:63], v[4:5] op_sel_hi:[0,1,1]
	v_pk_add_f32 v[8:9], v[0:1], v[4:5]
	ds_read_b128 v[4:7], v143 offset:36928
	ds_read_b128 v[38:41], v143 offset:36944
	ds_read_b128 v[56:59], v143 offset:38976
	ds_read_b128 v[60:63], v143 offset:38992
	s_waitcnt lgkmcnt(3)
	v_mov_b32_e32 v0, v4
	s_waitcnt lgkmcnt(1)
	v_mov_b32_e32 v1, v56
	v_mov_b32_e32 v56, v5
	v_pk_mul_f32 v[4:5], v[36:37], v[56:57] op_sel_hi:[0,1]
	v_pk_fma_f32 v[0:1], v[32:33], v[0:1], v[4:5] op_sel_hi:[0,1,1]
	v_mov_b32_e32 v4, v6
	v_mov_b32_e32 v5, v58
	v_pk_fma_f32 v[0:1], v[42:43], v[4:5], v[0:1] op_sel_hi:[0,1,1]
	v_mov_b32_e32 v58, v7
	v_pk_fma_f32 v[0:1], v[44:45], v[58:59], v[0:1] op_sel_hi:[0,1,1]
	v_mov_b32_e32 v4, v38
	s_waitcnt lgkmcnt(0)
	v_mov_b32_e32 v5, v60
	v_pk_fma_f32 v[0:1], v[48:49], v[4:5], v[0:1] op_sel_hi:[0,1,1]
	v_mov_b32_e32 v60, v39
	v_pk_fma_f32 v[0:1], v[50:51], v[60:61], v[0:1] op_sel_hi:[0,1,1]
	v_mov_b32_e32 v4, v40
	v_mov_b32_e32 v5, v62
	v_pk_fma_f32 v[0:1], v[52:53], v[4:5], v[0:1] op_sel_hi:[0,1,1]
	v_mov_b32_e32 v62, v41
	v_pk_fma_f32 v[0:1], v[54:55], v[62:63], v[0:1] op_sel_hi:[0,1,1]
	v_pk_add_f32 v[6:7], v[2:3], v[0:1]
	ds_read_b128 v[0:3], v143 offset:41024
	ds_read_b128 v[38:41], v143 offset:41040
	ds_read_b128 v[56:59], v143 offset:43072
	ds_read_b128 v[60:63], v143 offset:43088
	s_waitcnt lgkmcnt(3)
	v_mov_b32_e32 v4, v0
	s_waitcnt lgkmcnt(1)
	v_mov_b32_e32 v5, v56
	v_mov_b32_e32 v56, v1
	v_pk_mul_f32 v[0:1], v[36:37], v[56:57] op_sel_hi:[0,1]
	v_pk_fma_f32 v[0:1], v[32:33], v[4:5], v[0:1] op_sel_hi:[0,1,1]
	v_mov_b32_e32 v4, v2
	v_mov_b32_e32 v5, v58
	v_pk_fma_f32 v[0:1], v[42:43], v[4:5], v[0:1] op_sel_hi:[0,1,1]
	v_mov_b32_e32 v58, v3
	v_pk_fma_f32 v[0:1], v[44:45], v[58:59], v[0:1] op_sel_hi:[0,1,1]
	v_mov_b32_e32 v2, v38
	s_waitcnt lgkmcnt(0)
	v_mov_b32_e32 v3, v60
	v_pk_fma_f32 v[0:1], v[48:49], v[2:3], v[0:1] op_sel_hi:[0,1,1]
	v_mov_b32_e32 v60, v39
	v_pk_fma_f32 v[0:1], v[50:51], v[60:61], v[0:1] op_sel_hi:[0,1,1]
	v_mov_b32_e32 v2, v40
	v_mov_b32_e32 v3, v62
	v_pk_fma_f32 v[0:1], v[52:53], v[2:3], v[0:1] op_sel_hi:[0,1,1]
	v_mov_b32_e32 v62, v41
	v_pk_fma_f32 v[0:1], v[54:55], v[62:63], v[0:1] op_sel_hi:[0,1,1]
	v_pk_add_f32 v[2:3], v[26:27], v[0:1]
	ds_read_b128 v[26:29], v143 offset:45120
	ds_read_b128 v[38:41], v143 offset:45136
	ds_read_b128 v[56:59], v143 offset:47168
	ds_read_b128 v[60:63], v143 offset:47184
	s_waitcnt lgkmcnt(3)
	v_mov_b32_e32 v0, v26
	s_waitcnt lgkmcnt(1)
	v_mov_b32_e32 v1, v56
	v_mov_b32_e32 v56, v27
	v_pk_mul_f32 v[4:5], v[36:37], v[56:57] op_sel_hi:[0,1]
	v_pk_fma_f32 v[0:1], v[32:33], v[0:1], v[4:5] op_sel_hi:[0,1,1]
	v_mov_b32_e32 v4, v28
	v_mov_b32_e32 v5, v58
	v_pk_fma_f32 v[0:1], v[42:43], v[4:5], v[0:1] op_sel_hi:[0,1,1]
	v_mov_b32_e32 v58, v29
	v_pk_fma_f32 v[0:1], v[44:45], v[58:59], v[0:1] op_sel_hi:[0,1,1]
	v_mov_b32_e32 v4, v38
	s_waitcnt lgkmcnt(0)
; DI void phase_setup(const Params& p, char* lds) {
;     ...
;         for (int k8 = 0; k8 < 32; k8 += 8) {
;           float w[8];
; #pragma unroll
;           for (int u = 0; u < 8; ++u) w[u] = wp[(size_t)(k8 + u) * 3072];
; #pragma unroll
;           for (int bi = 0; bi < 24; ++bi) {
;             const float4 c0 = *(const float4*)(cs + bi * 512 + kp * 32 + k8), c1 = *(const float4*)(cs + bi * 512 + kp * 32 + k8 + 4);
;             acc[bi] += c0.x * w[0] + c0.y * w[1] + c0.z * w[2] + c0.w * w[3] + c1.x * w[4] + c1.y * w[5] + c1.z * w[6] + c1.w * w[7];
;           }
	v_mov_b32_e32 v5, v60
	v_pk_fma_f32 v[0:1], v[48:49], v[4:5], v[0:1] op_sel_hi:[0,1,1]
	v_mov_b32_e32 v60, v39
	v_pk_fma_f32 v[0:1], v[50:51], v[60:61], v[0:1] op_sel_hi:[0,1,1]
	v_mov_b32_e32 v4, v40
	v_mov_b32_e32 v5, v62
	v_pk_fma_f32 v[0:1], v[52:53], v[4:5], v[0:1] op_sel_hi:[0,1,1]
	v_add_co_u32_e32 v4, vcc, s0, v106
	s_mov_b32 s0, 0x4b000
	s_nop 0
	v_addc_co_u32_e32 v5, vcc, 0, v107, vcc
	v_add_co_u32_e32 v26, vcc, s0, v106
	s_mov_b32 s0, 0x4e000
	s_nop 0
	v_addc_co_u32_e32 v27, vcc, 0, v107, vcc
	v_mov_b32_e32 v62, v41
	v_add_co_u32_e32 v28, vcc, s0, v106
	v_pk_fma_f32 v[0:1], v[54:55], v[62:63], v[0:1] op_sel_hi:[0,1,1]
	s_nop 0
	v_addc_co_u32_e32 v29, vcc, 0, v107, vcc
	s_mov_b32 s0, 0x51000
	v_pk_add_f32 v[0:1], v[30:31], v[0:1]
	v_add_co_u32_e32 v30, vcc, s0, v106
	s_mov_b32 s0, 0x54000
	s_nop 0
	v_addc_co_u32_e32 v31, vcc, 0, v107, vcc
	v_add_co_u32_e32 v32, vcc, s0, v106
	s_waitcnt vmcnt(0)
	v_mov_b32_e32 v4, v234
	s_nop 0
	v_addc_co_u32_e32 v33, vcc, 0, v107, vcc
	v_mov_b32_e32 v26, v235
	s_mov_b32 s0, 0x57000
	v_add_co_u32_e32 v34, vcc, s0, v106
	v_mov_b32_e32 v28, v236
	s_nop 0
	v_addc_co_u32_e32 v35, vcc, 0, v107, vcc
	s_mov_b32 s0, 0x5a000
	v_mov_b32_e32 v30, v237
	v_add_co_u32_e32 v36, vcc, s0, v106
	v_mov_b32_e32 v32, v238
	s_nop 0
	v_addc_co_u32_e32 v37, vcc, 0, v107, vcc
	s_mov_b32 s0, 0x5d000
	v_mov_b32_e32 v34, v239
	v_add_co_u32_e32 v38, vcc, s0, v106
	v_mov_b32_e32 v36, v240
	s_nop 0
	v_addc_co_u32_e32 v39, vcc, 0, v107, vcc
	v_mov_b32_e32 v38, v241
	ds_read_b128 v[40:43], v143 offset:96
	ds_read_b128 v[44:47], v143 offset:112
	ds_read_b128 v[48:51], v143 offset:2144
	ds_read_b128 v[52:55], v143 offset:2160
	s_mov_b64 s[0:1], 0
	s_waitcnt lgkmcnt(3)
	v_mov_b32_e32 v56, v40
	s_and_b64 vcc, exec, s[64:65]
	s_waitcnt lgkmcnt(1)
	v_mov_b32_e32 v57, v48
	v_mov_b32_e32 v48, v41
	s_waitcnt vmcnt(6)
	v_pk_mul_f32 v[40:41], v[26:27], v[48:49] op_sel_hi:[0,1]
	v_pk_fma_f32 v[40:41], v[4:5], v[56:57], v[40:41] op_sel_hi:[0,1,1]
	v_mov_b32_e32 v48, v42
	v_mov_b32_e32 v49, v50
	s_waitcnt vmcnt(5)
	v_pk_fma_f32 v[40:41], v[28:29], v[48:49], v[40:41] op_sel_hi:[0,1,1]
	v_mov_b32_e32 v50, v43
	v_mov_b32_e32 v42, v44
	s_waitcnt lgkmcnt(0)
	v_mov_b32_e32 v43, v52
	s_waitcnt vmcnt(4)
	v_pk_fma_f32 v[40:41], v[30:31], v[50:51], v[40:41] op_sel_hi:[0,1,1]
	v_mov_b32_e32 v52, v45
	s_waitcnt vmcnt(3)
	v_pk_fma_f32 v[40:41], v[32:33], v[42:43], v[40:41] op_sel_hi:[0,1,1]
	v_mov_b32_e32 v42, v46
	v_mov_b32_e32 v43, v54
	v_mov_b32_e32 v54, v47
	s_waitcnt vmcnt(2)
	v_pk_fma_f32 v[40:41], v[34:35], v[52:53], v[40:41] op_sel_hi:[0,1,1]
	s_waitcnt vmcnt(1)
	v_pk_fma_f32 v[40:41], v[36:37], v[42:43], v[40:41] op_sel_hi:[0,1,1]
	s_waitcnt vmcnt(0)
	v_pk_fma_f32 v[40:41], v[38:39], v[54:55], v[40:41] op_sel_hi:[0,1,1]
	v_pk_add_f32 v[130:131], v[24:25], v[40:41]
	ds_read_b128 v[40:43], v143 offset:4192
	ds_read_b128 v[44:47], v143 offset:4208
	ds_read_b128 v[48:51], v143 offset:6240
	ds_read_b128 v[52:55], v143 offset:6256
	s_waitcnt lgkmcnt(3)
	v_mov_b32_e32 v24, v40
	s_waitcnt lgkmcnt(1)
	v_mov_b32_e32 v25, v48
	v_mov_b32_e32 v48, v41
	v_pk_mul_f32 v[40:41], v[26:27], v[48:49] op_sel_hi:[0,1]
	v_pk_fma_f32 v[24:25], v[4:5], v[24:25], v[40:41] op_sel_hi:[0,1,1]
	v_mov_b32_e32 v40, v42
	v_mov_b32_e32 v41, v50
	v_pk_fma_f32 v[24:25], v[28:29], v[40:41], v[24:25] op_sel_hi:[0,1,1]
	v_mov_b32_e32 v50, v43
	v_pk_fma_f32 v[24:25], v[30:31], v[50:51], v[24:25] op_sel_hi:[0,1,1]
	v_mov_b32_e32 v40, v44
	s_waitcnt lgkmcnt(0)
	v_mov_b32_e32 v41, v52
	v_pk_fma_f32 v[24:25], v[32:33], v[40:41], v[24:25] op_sel_hi:[0,1,1]
	v_mov_b32_e32 v52, v45
	v_pk_fma_f32 v[24:25], v[34:35], v[52:53], v[24:25] op_sel_hi:[0,1,1]
	v_mov_b32_e32 v40, v46
	v_mov_b32_e32 v41, v54
	v_pk_fma_f32 v[24:25], v[36:37], v[40:41], v[24:25] op_sel_hi:[0,1,1]
	v_mov_b32_e32 v54, v47
	v_pk_fma_f32 v[24:25], v[38:39], v[54:55], v[24:25] op_sel_hi:[0,1,1]
	v_pk_add_f32 v[126:127], v[22:23], v[24:25]
	ds_read_b128 v[22:25], v143 offset:8288
	ds_read_b128 v[40:43], v143 offset:8304
	ds_read_b128 v[44:47], v143 offset:10336
	ds_read_b128 v[48:51], v143 offset:10352
	s_waitcnt lgkmcnt(3)
	v_mov_b32_e32 v52, v22
	s_waitcnt lgkmcnt(1)
	v_mov_b32_e32 v53, v44
	v_mov_b32_e32 v44, v23
	v_pk_mul_f32 v[22:23], v[26:27], v[44:45] op_sel_hi:[0,1]
	v_pk_fma_f32 v[22:23], v[4:5], v[52:53], v[22:23] op_sel_hi:[0,1,1]
	v_mov_b32_e32 v44, v24
	v_mov_b32_e32 v45, v46
	v_pk_fma_f32 v[22:23], v[28:29], v[44:45], v[22:23] op_sel_hi:[0,1,1]
	v_mov_b32_e32 v46, v25
	v_pk_fma_f32 v[22:23], v[30:31], v[46:47], v[22:23] op_sel_hi:[0,1,1]
	v_mov_b32_e32 v24, v40
	s_waitcnt lgkmcnt(0)
	v_mov_b32_e32 v25, v48
	v_pk_fma_f32 v[22:23], v[32:33], v[24:25], v[22:23] op_sel_hi:[0,1,1]
	v_mov_b32_e32 v48, v41
	v_pk_fma_f32 v[22:23], v[34:35], v[48:49], v[22:23] op_sel_hi:[0,1,1]
	v_mov_b32_e32 v24, v42
	v_mov_b32_e32 v25, v50
	v_pk_fma_f32 v[22:23], v[36:37], v[24:25], v[22:23] op_sel_hi:[0,1,1]
	v_mov_b32_e32 v50, v43
	v_pk_fma_f32 v[22:23], v[38:39], v[50:51], v[22:23] op_sel_hi:[0,1,1]
	v_pk_add_f32 v[124:125], v[20:21], v[22:23]
	ds_read_b128 v[20:23], v143 offset:12384
	ds_read_b128 v[40:43], v143 offset:12400
	ds_read_b128 v[44:47], v143 offset:14432
	ds_read_b128 v[48:51], v143 offset:14448
	s_waitcnt lgkmcnt(3)
	v_mov_b32_e32 v24, v20
	s_waitcnt lgkmcnt(1)
	v_mov_b32_e32 v25, v44
	v_mov_b32_e32 v44, v21
	v_pk_mul_f32 v[20:21], v[26:27], v[44:45] op_sel_hi:[0,1]
	v_pk_fma_f32 v[20:21], v[4:5], v[24:25], v[20:21] op_sel_hi:[0,1,1]
	v_mov_b32_e32 v24, v22
	v_mov_b32_e32 v25, v46
	v_pk_fma_f32 v[20:21], v[28:29], v[24:25], v[20:21] op_sel_hi:[0,1,1]
	v_mov_b32_e32 v46, v23
	v_pk_fma_f32 v[20:21], v[30:31], v[46:47], v[20:21] op_sel_hi:[0,1,1]
	v_mov_b32_e32 v22, v40
	s_waitcnt lgkmcnt(0)
; DI void phase_setup(const Params& p, char* lds) {
;     ...
;           for (int bi = 0; bi < 24; ++bi) {
;             const float4 c0 = *(const float4*)(cs + bi * 512 + kp * 32 + k8), c1 = *(const float4*)(cs + bi * 512 + kp * 32 + k8 + 4);
;             acc[bi] += c0.x * w[0] + c0.y * w[1] + c0.z * w[2] + c0.w * w[3] + c1.x * w[4] + c1.y * w[5] + c1.z * w[6] + c1.w * w[7];
;           }
	v_mov_b32_e32 v23, v48
	v_pk_fma_f32 v[20:21], v[32:33], v[22:23], v[20:21] op_sel_hi:[0,1,1]
	v_mov_b32_e32 v48, v41
	v_pk_fma_f32 v[20:21], v[34:35], v[48:49], v[20:21] op_sel_hi:[0,1,1]
	v_mov_b32_e32 v22, v42
	v_mov_b32_e32 v23, v50
	v_pk_fma_f32 v[20:21], v[36:37], v[22:23], v[20:21] op_sel_hi:[0,1,1]
	v_mov_b32_e32 v50, v43
	v_pk_fma_f32 v[20:21], v[38:39], v[50:51], v[20:21] op_sel_hi:[0,1,1]
	v_pk_add_f32 v[128:129], v[18:19], v[20:21]
	ds_read_b128 v[18:21], v143 offset:16480
	ds_read_b128 v[22:25], v143 offset:16496
	ds_read_b128 v[40:43], v143 offset:18528
	ds_read_b128 v[44:47], v143 offset:18544
	s_waitcnt lgkmcnt(3)
	v_mov_b32_e32 v48, v18
	s_waitcnt lgkmcnt(1)
	v_mov_b32_e32 v49, v40
	v_mov_b32_e32 v40, v19
	v_pk_mul_f32 v[18:19], v[26:27], v[40:41] op_sel_hi:[0,1]
	v_pk_fma_f32 v[18:19], v[4:5], v[48:49], v[18:19] op_sel_hi:[0,1,1]
	v_mov_b32_e32 v40, v20
	v_mov_b32_e32 v41, v42
	v_pk_fma_f32 v[18:19], v[28:29], v[40:41], v[18:19] op_sel_hi:[0,1,1]
	v_mov_b32_e32 v42, v21
	v_pk_fma_f32 v[18:19], v[30:31], v[42:43], v[18:19] op_sel_hi:[0,1,1]
	v_mov_b32_e32 v20, v22
	s_waitcnt lgkmcnt(0)
	v_mov_b32_e32 v21, v44
	v_pk_fma_f32 v[18:19], v[32:33], v[20:21], v[18:19] op_sel_hi:[0,1,1]
	v_mov_b32_e32 v44, v23
	v_pk_fma_f32 v[18:19], v[34:35], v[44:45], v[18:19] op_sel_hi:[0,1,1]
	v_mov_b32_e32 v20, v24
	v_mov_b32_e32 v21, v46
	v_pk_fma_f32 v[18:19], v[36:37], v[20:21], v[18:19] op_sel_hi:[0,1,1]
	v_mov_b32_e32 v46, v25
	v_pk_fma_f32 v[18:19], v[38:39], v[46:47], v[18:19] op_sel_hi:[0,1,1]
	v_pk_add_f32 v[122:123], v[16:17], v[18:19]
	ds_read_b128 v[16:19], v143 offset:20576
	ds_read_b128 v[20:23], v143 offset:20592
	ds_read_b128 v[40:43], v143 offset:22624
	ds_read_b128 v[44:47], v143 offset:22640
	s_waitcnt lgkmcnt(3)
	v_mov_b32_e32 v24, v16
	s_waitcnt lgkmcnt(1)
	v_mov_b32_e32 v25, v40
	v_mov_b32_e32 v40, v17
	v_pk_mul_f32 v[16:17], v[26:27], v[40:41] op_sel_hi:[0,1]
	v_pk_fma_f32 v[16:17], v[4:5], v[24:25], v[16:17] op_sel_hi:[0,1,1]
	v_mov_b32_e32 v24, v18
	v_mov_b32_e32 v25, v42
	v_pk_fma_f32 v[16:17], v[28:29], v[24:25], v[16:17] op_sel_hi:[0,1,1]
	v_mov_b32_e32 v42, v19
	v_pk_fma_f32 v[16:17], v[30:31], v[42:43], v[16:17] op_sel_hi:[0,1,1]
	v_mov_b32_e32 v18, v20
	s_waitcnt lgkmcnt(0)
	v_mov_b32_e32 v19, v44
	v_pk_fma_f32 v[16:17], v[32:33], v[18:19], v[16:17] op_sel_hi:[0,1,1]
	v_mov_b32_e32 v44, v21
	v_pk_fma_f32 v[16:17], v[34:35], v[44:45], v[16:17] op_sel_hi:[0,1,1]
	v_mov_b32_e32 v18, v22
	v_mov_b32_e32 v19, v46
	v_pk_fma_f32 v[16:17], v[36:37], v[18:19], v[16:17] op_sel_hi:[0,1,1]
	v_mov_b32_e32 v46, v23
	v_pk_fma_f32 v[16:17], v[38:39], v[46:47], v[16:17] op_sel_hi:[0,1,1]
	v_pk_add_f32 v[120:121], v[14:15], v[16:17]
	ds_read_b128 v[14:17], v143 offset:24672
	ds_read_b128 v[18:21], v143 offset:24688
	ds_read_b128 v[22:25], v143 offset:26720
	ds_read_b128 v[40:43], v143 offset:26736
	s_waitcnt lgkmcnt(3)
	v_mov_b32_e32 v44, v14
	s_waitcnt lgkmcnt(1)
	v_mov_b32_e32 v45, v22
	v_mov_b32_e32 v22, v15
	v_pk_mul_f32 v[14:15], v[26:27], v[22:23] op_sel_hi:[0,1]
	v_pk_fma_f32 v[14:15], v[4:5], v[44:45], v[14:15] op_sel_hi:[0,1,1]
	v_mov_b32_e32 v22, v16
	v_mov_b32_e32 v23, v24
	v_pk_fma_f32 v[14:15], v[28:29], v[22:23], v[14:15] op_sel_hi:[0,1,1]
	v_mov_b32_e32 v24, v17
	v_pk_fma_f32 v[14:15], v[30:31], v[24:25], v[14:15] op_sel_hi:[0,1,1]
	v_mov_b32_e32 v16, v18
	s_waitcnt lgkmcnt(0)
	v_mov_b32_e32 v17, v40
	v_pk_fma_f32 v[14:15], v[32:33], v[16:17], v[14:15] op_sel_hi:[0,1,1]
	v_mov_b32_e32 v40, v19
	v_pk_fma_f32 v[14:15], v[34:35], v[40:41], v[14:15] op_sel_hi:[0,1,1]
	v_mov_b32_e32 v16, v20
	v_mov_b32_e32 v17, v42
	v_pk_fma_f32 v[14:15], v[36:37], v[16:17], v[14:15] op_sel_hi:[0,1,1]
	v_mov_b32_e32 v42, v21
	v_pk_fma_f32 v[14:15], v[38:39], v[42:43], v[14:15] op_sel_hi:[0,1,1]
	v_pk_add_f32 v[118:119], v[12:13], v[14:15]
	ds_read_b128 v[12:15], v143 offset:28768
	ds_read_b128 v[16:19], v143 offset:28784
	ds_read_b128 v[20:23], v143 offset:30816
	ds_read_b128 v[40:43], v143 offset:30832
	s_waitcnt lgkmcnt(3)
	v_mov_b32_e32 v24, v12
	s_waitcnt lgkmcnt(1)
	v_mov_b32_e32 v25, v20
	v_mov_b32_e32 v20, v13
	v_pk_mul_f32 v[12:13], v[26:27], v[20:21] op_sel_hi:[0,1]
	v_pk_fma_f32 v[12:13], v[4:5], v[24:25], v[12:13] op_sel_hi:[0,1,1]
	v_mov_b32_e32 v20, v14
	v_mov_b32_e32 v21, v22
	v_pk_fma_f32 v[12:13], v[28:29], v[20:21], v[12:13] op_sel_hi:[0,1,1]
	v_mov_b32_e32 v22, v15
	v_pk_fma_f32 v[12:13], v[30:31], v[22:23], v[12:13] op_sel_hi:[0,1,1]
	v_mov_b32_e32 v14, v16
	s_waitcnt lgkmcnt(0)
	v_mov_b32_e32 v15, v40
	v_pk_fma_f32 v[12:13], v[32:33], v[14:15], v[12:13] op_sel_hi:[0,1,1]
	v_mov_b32_e32 v40, v17
	v_pk_fma_f32 v[12:13], v[34:35], v[40:41], v[12:13] op_sel_hi:[0,1,1]
	v_mov_b32_e32 v14, v18
	v_mov_b32_e32 v15, v42
	v_pk_fma_f32 v[12:13], v[36:37], v[14:15], v[12:13] op_sel_hi:[0,1,1]
	v_mov_b32_e32 v42, v19
	v_pk_fma_f32 v[12:13], v[38:39], v[42:43], v[12:13] op_sel_hi:[0,1,1]
	v_pk_add_f32 v[116:117], v[10:11], v[12:13]
	ds_read_b128 v[10:13], v143 offset:32864
	ds_read_b128 v[14:17], v143 offset:32880
	ds_read_b128 v[18:21], v143 offset:34912
	ds_read_b128 v[22:25], v143 offset:34928
	s_waitcnt lgkmcnt(3)
	v_mov_b32_e32 v40, v10
	s_waitcnt lgkmcnt(1)
; DI void phase_setup(const Params& p, char* lds) {
;     ...
;           for (int bi = 0; bi < 24; ++bi) {
;             const float4 c0 = *(const float4*)(cs + bi * 512 + kp * 32 + k8), c1 = *(const float4*)(cs + bi * 512 + kp * 32 + k8 + 4);
;             acc[bi] += c0.x * w[0] + c0.y * w[1] + c0.z * w[2] + c0.w * w[3] + c1.x * w[4] + c1.y * w[5] + c1.z * w[6] + c1.w * w[7];
;           }
;         }
;       }
;       __syncthreads();
;       float* red = (float*)lds;
; #pragma unroll
;       for (int bi = 0; bi < 24; ++bi) red[(kp * 24 + bi) * 16 + col] = acc[bi];
;       __syncthreads();
;       float* mod = (float*)(p.ws + W_MOD);
;       for (int idx = tid; idx < 24 * 16; idx += 256) {
;         const int bi = idx >> 4, c2 = idx & 15;
;         float s = 0.f;
; #pragma unroll
;         for (int q = 0; q < 16; ++q) s += red[(q * 24 + bi) * 16 + c2];
;         mod[(size_t)(bi * 2 + layer) * 3072 + cc * 16 + c2] = s + p.b_ada[layer * 3072 + cc * 16 + c2];
	v_mov_b32_e32 v41, v18
	v_mov_b32_e32 v18, v11
	v_pk_mul_f32 v[10:11], v[26:27], v[18:19] op_sel_hi:[0,1]
	v_pk_fma_f32 v[10:11], v[4:5], v[40:41], v[10:11] op_sel_hi:[0,1,1]
	v_mov_b32_e32 v18, v12
	v_mov_b32_e32 v19, v20
	v_pk_fma_f32 v[10:11], v[28:29], v[18:19], v[10:11] op_sel_hi:[0,1,1]
	v_mov_b32_e32 v20, v13
	v_pk_fma_f32 v[10:11], v[30:31], v[20:21], v[10:11] op_sel_hi:[0,1,1]
	v_mov_b32_e32 v12, v14
	s_waitcnt lgkmcnt(0)
	v_mov_b32_e32 v13, v22
	v_pk_fma_f32 v[10:11], v[32:33], v[12:13], v[10:11] op_sel_hi:[0,1,1]
	v_mov_b32_e32 v22, v15
	v_pk_fma_f32 v[10:11], v[34:35], v[22:23], v[10:11] op_sel_hi:[0,1,1]
	v_mov_b32_e32 v12, v16
	v_mov_b32_e32 v13, v24
	v_pk_fma_f32 v[10:11], v[36:37], v[12:13], v[10:11] op_sel_hi:[0,1,1]
	v_mov_b32_e32 v24, v17
	v_pk_fma_f32 v[10:11], v[38:39], v[24:25], v[10:11] op_sel_hi:[0,1,1]
	v_pk_add_f32 v[112:113], v[8:9], v[10:11]
	ds_read_b128 v[8:11], v143 offset:36960
	ds_read_b128 v[12:15], v143 offset:36976
	ds_read_b128 v[16:19], v143 offset:39008
	ds_read_b128 v[20:23], v143 offset:39024
	s_waitcnt lgkmcnt(3)
	v_mov_b32_e32 v24, v8
	s_waitcnt lgkmcnt(1)
	v_mov_b32_e32 v25, v16
	v_mov_b32_e32 v16, v9
	v_pk_mul_f32 v[8:9], v[26:27], v[16:17] op_sel_hi:[0,1]
	v_pk_fma_f32 v[8:9], v[4:5], v[24:25], v[8:9] op_sel_hi:[0,1,1]
	v_mov_b32_e32 v16, v10
	v_mov_b32_e32 v17, v18
	v_pk_fma_f32 v[8:9], v[28:29], v[16:17], v[8:9] op_sel_hi:[0,1,1]
	v_mov_b32_e32 v18, v11
	v_pk_fma_f32 v[8:9], v[30:31], v[18:19], v[8:9] op_sel_hi:[0,1,1]
	v_mov_b32_e32 v10, v12
	s_waitcnt lgkmcnt(0)
	v_mov_b32_e32 v11, v20
	v_pk_fma_f32 v[8:9], v[32:33], v[10:11], v[8:9] op_sel_hi:[0,1,1]
	v_mov_b32_e32 v20, v13
	v_pk_fma_f32 v[8:9], v[34:35], v[20:21], v[8:9] op_sel_hi:[0,1,1]
	v_mov_b32_e32 v10, v14
	v_mov_b32_e32 v11, v22
	v_pk_fma_f32 v[8:9], v[36:37], v[10:11], v[8:9] op_sel_hi:[0,1,1]
	v_mov_b32_e32 v22, v15
	v_pk_fma_f32 v[8:9], v[38:39], v[22:23], v[8:9] op_sel_hi:[0,1,1]
	v_pk_add_f32 v[114:115], v[6:7], v[8:9]
	ds_read_b128 v[6:9], v143 offset:41056
	ds_read_b128 v[10:13], v143 offset:41072
	ds_read_b128 v[14:17], v143 offset:43104
	ds_read_b128 v[18:21], v143 offset:43120
	s_waitcnt lgkmcnt(3)
	v_mov_b32_e32 v22, v6
	s_waitcnt lgkmcnt(1)
	v_mov_b32_e32 v23, v14
	v_mov_b32_e32 v14, v7
	v_pk_mul_f32 v[6:7], v[26:27], v[14:15] op_sel_hi:[0,1]
	v_pk_fma_f32 v[6:7], v[4:5], v[22:23], v[6:7] op_sel_hi:[0,1,1]
	v_mov_b32_e32 v14, v8
	v_mov_b32_e32 v15, v16
	v_pk_fma_f32 v[6:7], v[28:29], v[14:15], v[6:7] op_sel_hi:[0,1,1]
	v_mov_b32_e32 v16, v9
	v_pk_fma_f32 v[6:7], v[30:31], v[16:17], v[6:7] op_sel_hi:[0,1,1]
	v_mov_b32_e32 v8, v10
	s_waitcnt lgkmcnt(0)
	v_mov_b32_e32 v9, v18
	v_pk_fma_f32 v[6:7], v[32:33], v[8:9], v[6:7] op_sel_hi:[0,1,1]
	v_mov_b32_e32 v18, v11
	v_pk_fma_f32 v[6:7], v[34:35], v[18:19], v[6:7] op_sel_hi:[0,1,1]
	v_mov_b32_e32 v8, v12
	v_mov_b32_e32 v9, v20
	v_pk_fma_f32 v[6:7], v[36:37], v[8:9], v[6:7] op_sel_hi:[0,1,1]
	v_mov_b32_e32 v20, v13
	v_pk_fma_f32 v[6:7], v[38:39], v[20:21], v[6:7] op_sel_hi:[0,1,1]
	v_pk_add_f32 v[110:111], v[2:3], v[6:7]
	ds_read_b128 v[6:9], v143 offset:45152
	ds_read_b128 v[10:13], v143 offset:45168
	ds_read_b128 v[14:17], v143 offset:47200
	ds_read_b128 v[18:21], v143 offset:47216
	s_waitcnt lgkmcnt(3)
	v_mov_b32_e32 v2, v6
	s_waitcnt lgkmcnt(1)
	v_mov_b32_e32 v3, v14
	v_mov_b32_e32 v14, v7
	v_pk_mul_f32 v[6:7], v[26:27], v[14:15] op_sel_hi:[0,1]
	v_pk_fma_f32 v[2:3], v[4:5], v[2:3], v[6:7] op_sel_hi:[0,1,1]
	v_mov_b32_e32 v4, v8
	v_mov_b32_e32 v5, v16
	v_pk_fma_f32 v[2:3], v[28:29], v[4:5], v[2:3] op_sel_hi:[0,1,1]
	v_mov_b32_e32 v16, v9
	v_pk_fma_f32 v[2:3], v[30:31], v[16:17], v[2:3] op_sel_hi:[0,1,1]
	v_mov_b32_e32 v4, v10
	s_waitcnt lgkmcnt(0)
	v_mov_b32_e32 v5, v18
	v_pk_fma_f32 v[2:3], v[32:33], v[4:5], v[2:3] op_sel_hi:[0,1,1]
	v_mov_b32_e32 v18, v11
	v_pk_fma_f32 v[2:3], v[34:35], v[18:19], v[2:3] op_sel_hi:[0,1,1]
	v_mov_b32_e32 v4, v12
	v_mov_b32_e32 v5, v20
	v_pk_fma_f32 v[2:3], v[36:37], v[4:5], v[2:3] op_sel_hi:[0,1,1]
	v_mov_b32_e32 v20, v13
	v_pk_fma_f32 v[2:3], v[38:39], v[20:21], v[2:3] op_sel_hi:[0,1,1]
	v_pk_add_f32 v[108:109], v[0:1], v[2:3]
	s_cbranch_vccz .LBB0_73
	v_add_u32_e32 v0, 0x400, v191
	s_barrier
	ds_write2_b32 v191, v130, v131 offset1:16
	ds_write2_b32 v191, v126, v127 offset0:32 offset1:48
	ds_write2_b32 v191, v124, v125 offset0:64 offset1:80
	ds_write2_b32 v191, v128, v129 offset0:96 offset1:112
	ds_write2_b32 v191, v122, v123 offset0:128 offset1:144
	ds_write2_b32 v191, v120, v121 offset0:160 offset1:176
	ds_write2_b32 v191, v118, v119 offset0:192 offset1:208
	ds_write2_b32 v191, v116, v117 offset0:224 offset1:240
	ds_write2_b32 v0, v112, v113 offset1:16
	ds_write2_b32 v0, v114, v115 offset0:32 offset1:48
	ds_write2_b32 v0, v110, v111 offset0:64 offset1:80
	ds_write2_b32 v0, v108, v109 offset0:96 offset1:112
	v_mad_u64_u32 v[0:1], s[0:1], v98, s93, v[100:101]
	v_or_b32_e32 v0, v0, v135
	v_add_u32_e32 v4, v199, v98
	v_lshlrev_b64 v[2:3], 2, v[100:101]
	v_ashrrev_i32_e32 v1, 31, v0
	v_mad_i64_i32 v[2:3], s[0:1], v4, s92, v[2:3]
	v_lshl_add_u64 v[0:1], v[0:1], 2, s[18:19]
	v_lshl_add_u64 v[2:3], v[96:97], 0, v[2:3]
	s_mov_b64 s[0:1], 0
	v_mov_b32_e32 v4, v200
	v_mov_b32_e32 v5, v198
	s_waitcnt lgkmcnt(0)
	s_barrier
